# GEMM K-loops: loop-edge rotation - loop-control scalar work issued in the shadow of the last MFMA block, back edge goes from the barrier straight to the LDS reads
# speedup vs baseline: 1.0121x; 1.0076x over previous
; #define PG8_STAGE(bufoff, gbase, voff) do { _Pragma("unroll") for (int _i = 0; _i < 2; ++_i) \
;         __builtin_amdgcn_global_load_lds((const unsigned*)((const char*)(gbase) + (voff)[_i]), (LAS unsigned*)(lds + (bufoff) + ldsw + _i * 8192), 16, 0, 0); } while (0)
; #define PG8_LDA(dst, b, h) do { _Pragma("unroll") for (int m = 0; m < 4; ++m) _Pragma("unroll") for (int k = 0; k < 2; ++k) dst[m][k] = *(const LAS bf16x8*)(lds + PG8_SA(b, h) + aoff + m * 2048 + k * 1024); } while (0)
; #define PG8_LDB(dst, b, h) do { _Pragma("unroll") for (int n = 0; n < 2; ++n) _Pragma("unroll") for (int k = 0; k < 2; ++k) dst[n][k] = *(const LAS bf16x8*)(lds + PG8_SB(b, h) + boff + n * 2048 + k * 1024); } while (0)
; #define PG8_MMA(ai, bj, At, Bt) do { __builtin_amdgcn_s_setprio(1); _Pragma("unroll") for (int m = 0; m < 4; ++m) _Pragma("unroll") for (int n = 0; n < 2; ++n) _Pragma("unroll") for (int k = 0; k < 2; ++k) \
;         acc[ai][bj][m][n] = __builtin_amdgcn_mfma_f32_16x16x32_bf16(Bt[n][k], At[m][k], acc[ai][bj][m][n], 0, 0, 0); __builtin_amdgcn_s_setprio(0); } while (0)
; #define PG8_WAIT_V(n) asm volatile("s_waitcnt vmcnt(" #n ")" ::: "memory")
; #define PG8_WAIT_L(n) asm volatile("s_waitcnt lgkmcnt(" #n ")" ::: "memory")
; #define PG8_BAR __builtin_amdgcn_s_barrier()
; #define PG8_SCHED __builtin_amdgcn_sched_barrier(0)
; template <class Epi, bool ALIGN_EPI, bool SP2>
; __device__ __forceinline__ void gemm_phase(LAS unsigned char* lds, const Gemm g, const StaticOrder& S, const Epi& E, const int tid) {
;     ...
;             PG8_LDB(B0, 0, 0); PG8_LDB(B1, 0, 1); PG8_SCHED; PG8_LDA(At, 0, 0); PG8_STAGE(PG8_SA(1, 1), a1 + hstep, voffA);
;             PG8_WAIT_V(8); PG8_WAIT_L(0); PG8_BAR; PG8_MMA(0, 0, At, B0); PG8_MMA(0, 1, At, B1); PG8_BAR; PG8_SCHED;
;             PG8_LDA(At, 0, 1); PG8_STAGE(PG8_SB(0, 0), b2, voffB); PG8_STAGE(PG8_SB(0, 1), b2 + hstep, voffB); PG8_STAGE(PG8_SA(0, 0), a2, voffA);
;             PG8_WAIT_V(8); PG8_WAIT_L(0); PG8_BAR; PG8_MMA(1, 0, At, B0); PG8_MMA(1, 1, At, B1); PG8_BAR; PG8_SCHED;
.Lk311_head:
	v_add_u32_e32 v140, s28, v187
	v_add_u32_e32 v152, s29, v187
	ds_read_b128 v[128:131], v140
	ds_read_b128 v[132:135], v140 offset:1024
	ds_read_b128 v[136:139], v140 offset:2048
	ds_read_b128 v[140:143], v140 offset:3072
	ds_read_b128 v[144:147], v152
	ds_read_b128 v[148:151], v152 offset:1024
	ds_read_b128 v[172:175], v152 offset:2048
	ds_read_b128 v[176:179], v152 offset:3072
	v_lshl_add_u64 v[152:153], s[0:1], 0, v[168:169]
	s_add_i32 m0, s41, 0xc000
	ds_read_b128 v[180:183], v191
	ds_read_b128 v[208:211], v191 offset:1024
	ds_read_b128 v[214:217], v191 offset:2048
	ds_read_b128 v[218:221], v191 offset:3072
	ds_read_b128 v[222:225], v191 offset:4096
	ds_read_b128 v[226:229], v191 offset:5120
	ds_read_b128 v[230:233], v191 offset:6144
	ds_read_b128 v[234:237], v191 offset:7168
	global_load_lds_dwordx4 v[152:153], off
	v_lshl_add_u64 v[152:153], s[0:1], 0, v[170:171]
	s_add_i32 m0, s41, 0xe000
	s_nop 0
	global_load_lds_dwordx4 v[152:153], off
	s_waitcnt vmcnt(8)
	s_waitcnt lgkmcnt(0)
	s_barrier
	s_setprio 1
	s_waitcnt lgkmcnt(0)
	v_mfma_f32_16x16x32_bf16 v[124:127], v[128:131], v[180:183], v[124:127]
	v_mfma_f32_16x16x32_bf16 v[120:123], v[136:139], v[180:183], v[120:123]
	v_mfma_f32_16x16x32_bf16 v[108:111], v[128:131], v[214:217], v[108:111]
	v_mfma_f32_16x16x32_bf16 v[104:107], v[136:139], v[214:217], v[104:107]
	v_mfma_f32_16x16x32_bf16 v[92:95], v[128:131], v[222:225], v[92:95]
	v_mfma_f32_16x16x32_bf16 v[88:91], v[136:139], v[222:225], v[88:91]
	v_mfma_f32_16x16x32_bf16 v[76:79], v[128:131], v[230:233], v[76:79]
	v_mfma_f32_16x16x32_bf16 v[72:75], v[136:139], v[230:233], v[72:75]
	v_mfma_f32_16x16x32_bf16 v[124:127], v[132:135], v[208:211], v[124:127]
	v_mfma_f32_16x16x32_bf16 v[120:123], v[140:143], v[208:211], v[120:123]
	v_mfma_f32_16x16x32_bf16 v[108:111], v[132:135], v[218:221], v[108:111]
	v_mfma_f32_16x16x32_bf16 v[104:107], v[140:143], v[218:221], v[104:107]
	v_mfma_f32_16x16x32_bf16 v[92:95], v[132:135], v[226:229], v[92:95]
	v_mfma_f32_16x16x32_bf16 v[88:91], v[140:143], v[226:229], v[88:91]
	v_mfma_f32_16x16x32_bf16 v[76:79], v[132:135], v[234:237], v[76:79]
	v_mfma_f32_16x16x32_bf16 v[72:75], v[140:143], v[234:237], v[72:75]
	s_setprio 0
	s_setprio 1
	v_mfma_f32_16x16x32_bf16 v[116:119], v[144:147], v[180:183], v[116:119]
	v_mfma_f32_16x16x32_bf16 v[112:115], v[172:175], v[180:183], v[112:115]
	v_mfma_f32_16x16x32_bf16 v[100:103], v[144:147], v[214:217], v[100:103]
	v_mfma_f32_16x16x32_bf16 v[96:99], v[172:175], v[214:217], v[96:99]
	v_mfma_f32_16x16x32_bf16 v[84:87], v[144:147], v[222:225], v[84:87]
	v_mfma_f32_16x16x32_bf16 v[80:83], v[172:175], v[222:225], v[80:83]
	v_mfma_f32_16x16x32_bf16 v[68:71], v[144:147], v[230:233], v[68:71]
	v_mfma_f32_16x16x32_bf16 v[64:67], v[172:175], v[230:233], v[64:67]
	v_mfma_f32_16x16x32_bf16 v[116:119], v[148:151], v[208:211], v[116:119]
	v_mfma_f32_16x16x32_bf16 v[112:115], v[176:179], v[208:211], v[112:115]
	v_mfma_f32_16x16x32_bf16 v[100:103], v[148:151], v[218:221], v[100:103]
	v_mfma_f32_16x16x32_bf16 v[96:99], v[176:179], v[218:221], v[96:99]
	v_mfma_f32_16x16x32_bf16 v[84:87], v[148:151], v[226:229], v[84:87]
	v_mfma_f32_16x16x32_bf16 v[80:83], v[176:179], v[226:229], v[80:83]
	v_mfma_f32_16x16x32_bf16 v[68:71], v[148:151], v[234:237], v[68:71]
	v_mfma_f32_16x16x32_bf16 v[64:67], v[176:179], v[234:237], v[64:67]
	s_setprio 0
	s_barrier
	s_add_i32 s28, s28, s43
	v_lshl_add_u64 v[152:153], s[26:27], 0, v[156:157]
	s_mov_b32 m0, s28
	ds_read_b128 v[180:183], v191 offset:16384
	ds_read_b128 v[208:211], v191 offset:17408
	ds_read_b128 v[214:217], v191 offset:18432
	ds_read_b128 v[218:221], v191 offset:19456
	ds_read_b128 v[222:225], v191 offset:20480
	ds_read_b128 v[226:229], v191 offset:21504
	ds_read_b128 v[230:233], v191 offset:22528
	ds_read_b128 v[234:237], v191 offset:23552
	global_load_lds_dwordx4 v[152:153], off
	s_add_i32 m0, s28, 0x2000
	v_lshl_add_u64 v[184:185], s[26:27], 0, v[154:155]
	s_add_u32 s26, s26, s36
	s_addc_u32 s27, s27, 0
	s_add_i32 s28, s29, s43
	global_load_lds_dwordx4 v[184:185], off
	v_lshl_add_u64 v[188:189], s[26:27], 0, v[156:157]
	s_mov_b32 m0, s28
	v_lshl_add_u64 v[192:193], s[26:27], 0, v[154:155]
	global_load_lds_dwordx4 v[188:189], off
	s_add_i32 m0, s28, 0x2000
	v_lshl_add_u64 v[238:239], s[18:19], 0, v[156:157]
	global_load_lds_dwordx4 v[192:193], off
	s_mov_b32 m0, s41
	v_lshl_add_u64 v[240:241], s[18:19], 0, v[154:155]
	global_load_lds_dwordx4 v[238:239], off
	s_mov_b32 m0, s97
	s_nop 0
	global_load_lds_dwordx4 v[240:241], off
	s_waitcnt vmcnt(8)
	s_waitcnt lgkmcnt(0)
	s_barrier
; #define PG8_STAGE(bufoff, gbase, voff) do { _Pragma("unroll") for (int _i = 0; _i < 2; ++_i) \
;         __builtin_amdgcn_global_load_lds((const unsigned*)((const char*)(gbase) + (voff)[_i]), (LAS unsigned*)(lds + (bufoff) + ldsw + _i * 8192), 16, 0, 0); } while (0)
; #define PG8_LDA(dst, b, h) do { _Pragma("unroll") for (int m = 0; m < 4; ++m) _Pragma("unroll") for (int k = 0; k < 2; ++k) dst[m][k] = *(const LAS bf16x8*)(lds + PG8_SA(b, h) + aoff + m * 2048 + k * 1024); } while (0)
; #define PG8_LDB(dst, b, h) do { _Pragma("unroll") for (int n = 0; n < 2; ++n) _Pragma("unroll") for (int k = 0; k < 2; ++k) dst[n][k] = *(const LAS bf16x8*)(lds + PG8_SB(b, h) + boff + n * 2048 + k * 1024); } while (0)
; #define PG8_MMA(ai, bj, At, Bt) do { __builtin_amdgcn_s_setprio(1); _Pragma("unroll") for (int m = 0; m < 4; ++m) _Pragma("unroll") for (int n = 0; n < 2; ++n) _Pragma("unroll") for (int k = 0; k < 2; ++k) \
;         acc[ai][bj][m][n] = __builtin_amdgcn_mfma_f32_16x16x32_bf16(Bt[n][k], At[m][k], acc[ai][bj][m][n], 0, 0, 0); __builtin_amdgcn_s_setprio(0); } while (0)
; #define PG8_WAIT_V(n) asm volatile("s_waitcnt vmcnt(" #n ")" ::: "memory")
; #define PG8_WAIT_L(n) asm volatile("s_waitcnt lgkmcnt(" #n ")" ::: "memory")
; #define PG8_BAR __builtin_amdgcn_s_barrier()
; #define PG8_SCHED __builtin_amdgcn_sched_barrier(0)
; template <class Epi, bool ALIGN_EPI, bool SP2>
; __device__ __forceinline__ void gemm_phase(LAS unsigned char* lds, const Gemm g, const StaticOrder& S, const Epi& E, const int tid) {
;     ...
;             PG8_LDA(At, 0, 1); PG8_STAGE(PG8_SB(0, 0), b2, voffB); PG8_STAGE(PG8_SB(0, 1), b2 + hstep, voffB); PG8_STAGE(PG8_SA(0, 0), a2, voffA);
;             PG8_WAIT_V(8); PG8_WAIT_L(0); PG8_BAR; PG8_MMA(1, 0, At, B0); PG8_MMA(1, 1, At, B1); PG8_BAR; PG8_SCHED;
;             PG8_LDB(B0, 1, 0); PG8_LDB(B1, 1, 1); PG8_SCHED; PG8_LDA(At, 1, 0); PG8_STAGE(PG8_SA(0, 1), a2 + hstep, voffA);
;             PG8_WAIT_V(8); PG8_WAIT_L(0); PG8_BAR; PG8_MMA(0, 0, At, B0); PG8_MMA(0, 1, At, B1); PG8_BAR; PG8_SCHED;
;             PG8_LDA(At, 1, 1); PG8_STAGE(PG8_SB(1, 0), b3, voffB); PG8_STAGE(PG8_SB(1, 1), b3 + hstep, voffB); PG8_STAGE(PG8_SA(1, 0), a3, voffA);
	s_setprio 1
	s_waitcnt lgkmcnt(0)
	v_mfma_f32_16x16x32_bf16 v[60:63], v[128:131], v[180:183], v[60:63]
	v_mfma_f32_16x16x32_bf16 v[56:59], v[136:139], v[180:183], v[56:59]
	v_mfma_f32_16x16x32_bf16 v[44:47], v[128:131], v[214:217], v[44:47]
	v_mfma_f32_16x16x32_bf16 v[40:43], v[136:139], v[214:217], v[40:43]
	v_mfma_f32_16x16x32_bf16 v[28:31], v[128:131], v[222:225], v[28:31]
	v_mfma_f32_16x16x32_bf16 v[24:27], v[136:139], v[222:225], v[24:27]
	v_mfma_f32_16x16x32_bf16 v[12:15], v[128:131], v[230:233], v[12:15]
	v_mfma_f32_16x16x32_bf16 v[8:11], v[136:139], v[230:233], v[8:11]
	v_mfma_f32_16x16x32_bf16 v[60:63], v[132:135], v[208:211], v[60:63]
	v_mfma_f32_16x16x32_bf16 v[56:59], v[140:143], v[208:211], v[56:59]
	v_mfma_f32_16x16x32_bf16 v[44:47], v[132:135], v[218:221], v[44:47]
	v_mfma_f32_16x16x32_bf16 v[40:43], v[140:143], v[218:221], v[40:43]
	v_mfma_f32_16x16x32_bf16 v[28:31], v[132:135], v[226:229], v[28:31]
	v_mfma_f32_16x16x32_bf16 v[24:27], v[140:143], v[226:229], v[24:27]
	v_mfma_f32_16x16x32_bf16 v[12:15], v[132:135], v[234:237], v[12:15]
	v_mfma_f32_16x16x32_bf16 v[8:11], v[140:143], v[234:237], v[8:11]
	s_setprio 0
	s_setprio 1
	v_mfma_f32_16x16x32_bf16 v[52:55], v[144:147], v[180:183], v[52:55]
	v_mfma_f32_16x16x32_bf16 v[48:51], v[172:175], v[180:183], v[48:51]
	v_mfma_f32_16x16x32_bf16 v[36:39], v[144:147], v[214:217], v[36:39]
	v_mfma_f32_16x16x32_bf16 v[32:35], v[172:175], v[214:217], v[32:35]
	v_mfma_f32_16x16x32_bf16 v[20:23], v[144:147], v[222:225], v[20:23]
	v_mfma_f32_16x16x32_bf16 v[16:19], v[172:175], v[222:225], v[16:19]
	v_mfma_f32_16x16x32_bf16 v[4:7], v[144:147], v[230:233], v[4:7]
	v_mfma_f32_16x16x32_bf16 v[0:3], v[172:175], v[230:233], v[0:3]
	v_mfma_f32_16x16x32_bf16 v[52:55], v[148:151], v[208:211], v[52:55]
	v_mfma_f32_16x16x32_bf16 v[48:51], v[176:179], v[208:211], v[48:51]
	v_mfma_f32_16x16x32_bf16 v[36:39], v[148:151], v[218:221], v[36:39]
	v_mfma_f32_16x16x32_bf16 v[32:35], v[176:179], v[218:221], v[32:35]
	v_mfma_f32_16x16x32_bf16 v[20:23], v[148:151], v[226:229], v[20:23]
	v_mfma_f32_16x16x32_bf16 v[16:19], v[176:179], v[226:229], v[16:19]
	v_mfma_f32_16x16x32_bf16 v[4:7], v[148:151], v[234:237], v[4:7]
	v_mfma_f32_16x16x32_bf16 v[0:3], v[176:179], v[234:237], v[0:3]
	s_setprio 0
	s_barrier
	s_add_i32 s26, 0, 0x18000
	s_add_i32 s27, 0, 0x1c000
	v_add_u32_e32 v140, s26, v187
	v_add_u32_e32 v160, s27, v187
	ds_read_b128 v[128:131], v140
	ds_read_b128 v[132:135], v140 offset:1024
	ds_read_b128 v[136:139], v140 offset:2048
	ds_read_b128 v[140:143], v140 offset:3072
	ds_read_b128 v[144:147], v160
	ds_read_b128 v[148:151], v160 offset:1024
	ds_read_b128 v[172:175], v160 offset:2048
	ds_read_b128 v[176:179], v160 offset:3072
	s_add_u32 s18, s18, s36
	s_addc_u32 s19, s19, 0
	s_mov_b32 m0, s14
	v_lshl_add_u64 v[242:243], s[18:19], 0, v[156:157]
	ds_read_b128 v[180:183], v191 offset:32768
	ds_read_b128 v[208:211], v191 offset:33792
	ds_read_b128 v[214:217], v191 offset:34816
	ds_read_b128 v[218:221], v191 offset:35840
	ds_read_b128 v[222:225], v191 offset:36864
	ds_read_b128 v[226:229], v191 offset:37888
	ds_read_b128 v[230:233], v191 offset:38912
	ds_read_b128 v[234:237], v191 offset:39936
	global_load_lds_dwordx4 v[242:243], off
	v_lshl_add_u64 v[242:243], s[18:19], 0, v[154:155]
	s_mov_b32 m0, s15
	s_nop 0
	global_load_lds_dwordx4 v[242:243], off
	s_waitcnt vmcnt(8)
	s_waitcnt lgkmcnt(0)
	s_barrier
	s_setprio 1
	s_waitcnt lgkmcnt(0)
	v_mfma_f32_16x16x32_bf16 v[124:127], v[128:131], v[180:183], v[124:127]
	v_mfma_f32_16x16x32_bf16 v[120:123], v[136:139], v[180:183], v[120:123]
	v_mfma_f32_16x16x32_bf16 v[108:111], v[128:131], v[214:217], v[108:111]
	v_mfma_f32_16x16x32_bf16 v[104:107], v[136:139], v[214:217], v[104:107]
	v_mfma_f32_16x16x32_bf16 v[92:95], v[128:131], v[222:225], v[92:95]
	v_mfma_f32_16x16x32_bf16 v[88:91], v[136:139], v[222:225], v[88:91]
	v_mfma_f32_16x16x32_bf16 v[76:79], v[128:131], v[230:233], v[76:79]
	v_mfma_f32_16x16x32_bf16 v[72:75], v[136:139], v[230:233], v[72:75]
	v_mfma_f32_16x16x32_bf16 v[124:127], v[132:135], v[208:211], v[124:127]
	v_mfma_f32_16x16x32_bf16 v[120:123], v[140:143], v[208:211], v[120:123]
	v_mfma_f32_16x16x32_bf16 v[108:111], v[132:135], v[218:221], v[108:111]
	v_mfma_f32_16x16x32_bf16 v[104:107], v[140:143], v[218:221], v[104:107]
	v_mfma_f32_16x16x32_bf16 v[92:95], v[132:135], v[226:229], v[92:95]
	v_mfma_f32_16x16x32_bf16 v[88:91], v[140:143], v[226:229], v[88:91]
	v_mfma_f32_16x16x32_bf16 v[76:79], v[132:135], v[234:237], v[76:79]
	v_mfma_f32_16x16x32_bf16 v[72:75], v[140:143], v[234:237], v[72:75]
	s_setprio 0
	s_setprio 1
	v_mfma_f32_16x16x32_bf16 v[116:119], v[144:147], v[180:183], v[116:119]
	v_mfma_f32_16x16x32_bf16 v[112:115], v[172:175], v[180:183], v[112:115]
	v_mfma_f32_16x16x32_bf16 v[100:103], v[144:147], v[214:217], v[100:103]
	v_mfma_f32_16x16x32_bf16 v[96:99], v[172:175], v[214:217], v[96:99]
	v_mfma_f32_16x16x32_bf16 v[84:87], v[144:147], v[222:225], v[84:87]
	v_mfma_f32_16x16x32_bf16 v[80:83], v[172:175], v[222:225], v[80:83]
	v_mfma_f32_16x16x32_bf16 v[68:71], v[144:147], v[230:233], v[68:71]
	v_mfma_f32_16x16x32_bf16 v[64:67], v[172:175], v[230:233], v[64:67]
	v_mfma_f32_16x16x32_bf16 v[116:119], v[148:151], v[208:211], v[116:119]
	v_mfma_f32_16x16x32_bf16 v[112:115], v[176:179], v[208:211], v[112:115]
	v_mfma_f32_16x16x32_bf16 v[100:103], v[148:151], v[218:221], v[100:103]
	v_mfma_f32_16x16x32_bf16 v[96:99], v[176:179], v[218:221], v[96:99]
	v_mfma_f32_16x16x32_bf16 v[84:87], v[148:151], v[226:229], v[84:87]
	v_mfma_f32_16x16x32_bf16 v[80:83], v[176:179], v[226:229], v[80:83]
	v_mfma_f32_16x16x32_bf16 v[68:71], v[148:151], v[234:237], v[68:71]
	v_mfma_f32_16x16x32_bf16 v[64:67], v[176:179], v[234:237], v[64:67]
	s_setprio 0
	s_barrier
; #define PG8_STAGE(bufoff, gbase, voff) do { _Pragma("unroll") for (int _i = 0; _i < 2; ++_i) \
;         __builtin_amdgcn_global_load_lds((const unsigned*)((const char*)(gbase) + (voff)[_i]), (LAS unsigned*)(lds + (bufoff) + ldsw + _i * 8192), 16, 0, 0); } while (0)
; #define PG8_LDA(dst, b, h) do { _Pragma("unroll") for (int m = 0; m < 4; ++m) _Pragma("unroll") for (int k = 0; k < 2; ++k) dst[m][k] = *(const LAS bf16x8*)(lds + PG8_SA(b, h) + aoff + m * 2048 + k * 1024); } while (0)
; #define PG8_MMA(ai, bj, At, Bt) do { __builtin_amdgcn_s_setprio(1); _Pragma("unroll") for (int m = 0; m < 4; ++m) _Pragma("unroll") for (int n = 0; n < 2; ++n) _Pragma("unroll") for (int k = 0; k < 2; ++k) \
;         acc[ai][bj][m][n] = __builtin_amdgcn_mfma_f32_16x16x32_bf16(Bt[n][k], At[m][k], acc[ai][bj][m][n], 0, 0, 0); __builtin_amdgcn_s_setprio(0); } while (0)
; #define PG8_WAIT_V(n) asm volatile("s_waitcnt vmcnt(" #n ")" ::: "memory")
; #define PG8_WAIT_L(n) asm volatile("s_waitcnt lgkmcnt(" #n ")" ::: "memory")
; #define PG8_BAR __builtin_amdgcn_s_barrier()
; #define PG8_SCHED __builtin_amdgcn_sched_barrier(0)
; template <class Epi, bool ALIGN_EPI, bool SP2>
; __device__ __forceinline__ void gemm_phase(LAS unsigned char* lds, const Gemm g, const StaticOrder& S, const Epi& E, const int tid) {
;     ...
;         for (int t = 0; t < nt; t += 2) {
;             const bool last = (t == nt - 2);
;             const char* a1 = cA + (size_t)(t + 1) * kstep;
;             const char* a2 = last ? nA : cA + (size_t)(t + 2) * kstep; const char* b2 = last ? nB : cB + (size_t)(t + 2) * kstep;
;             const char* a3 = a2 + kstep; const char* b3 = b2 + kstep;
;     ...
;             PG8_LDA(At, 1, 1); PG8_STAGE(PG8_SB(1, 0), b3, voffB); PG8_STAGE(PG8_SB(1, 1), b3 + hstep, voffB); PG8_STAGE(PG8_SA(1, 0), a3, voffA);
;             PG8_WAIT_V(8); PG8_WAIT_L(0); PG8_BAR; PG8_MMA(1, 0, At, B0); PG8_MMA(1, 1, At, B1); PG8_BAR; PG8_SCHED;
	s_add_i32 s18, s26, s43
	v_lshl_add_u64 v[152:153], v[152:153], 0, s[8:9]
	s_mov_b32 m0, s18
	ds_read_b128 v[180:183], v191 offset:49152
	ds_read_b128 v[208:211], v191 offset:50176
	ds_read_b128 v[214:217], v191 offset:51200
	ds_read_b128 v[218:221], v191 offset:52224
	ds_read_b128 v[222:225], v191 offset:53248
	ds_read_b128 v[226:229], v191 offset:54272
	ds_read_b128 v[230:233], v191 offset:55296
	ds_read_b128 v[234:237], v191 offset:56320
	global_load_lds_dwordx4 v[152:153], off
	v_lshl_add_u64 v[152:153], v[184:185], 0, s[8:9]
	s_add_i32 m0, s18, 0x2000
	s_add_i32 s18, s27, s43
	global_load_lds_dwordx4 v[152:153], off
	v_lshl_add_u64 v[152:153], v[188:189], 0, s[8:9]
	s_mov_b32 m0, s18
	s_nop 0
	global_load_lds_dwordx4 v[152:153], off
	v_lshl_add_u64 v[152:153], v[192:193], 0, s[8:9]
	s_add_i32 m0, s18, 0x2000
	s_nop 0
	global_load_lds_dwordx4 v[152:153], off
	v_lshl_add_u64 v[152:153], v[238:239], 0, s[8:9]
	s_mov_b32 m0, s54
	s_nop 0
	global_load_lds_dwordx4 v[152:153], off
	v_lshl_add_u64 v[152:153], v[240:241], 0, s[8:9]
	s_mov_b32 m0, s55
	s_nop 0
	global_load_lds_dwordx4 v[152:153], off
	s_waitcnt vmcnt(8)
	s_waitcnt lgkmcnt(0)
	s_barrier
	s_setprio 1
	s_waitcnt lgkmcnt(0)
	v_mfma_f32_16x16x32_bf16 v[60:63], v[128:131], v[180:183], v[60:63]
	v_mfma_f32_16x16x32_bf16 v[56:59], v[136:139], v[180:183], v[56:59]
	v_mfma_f32_16x16x32_bf16 v[44:47], v[128:131], v[214:217], v[44:47]
	v_mfma_f32_16x16x32_bf16 v[40:43], v[136:139], v[214:217], v[40:43]
	v_mfma_f32_16x16x32_bf16 v[28:31], v[128:131], v[222:225], v[28:31]
	v_mfma_f32_16x16x32_bf16 v[24:27], v[136:139], v[222:225], v[24:27]
	v_mfma_f32_16x16x32_bf16 v[12:15], v[128:131], v[230:233], v[12:15]
	v_mfma_f32_16x16x32_bf16 v[8:11], v[136:139], v[230:233], v[8:11]
	v_mfma_f32_16x16x32_bf16 v[60:63], v[132:135], v[208:211], v[60:63]
	v_mfma_f32_16x16x32_bf16 v[56:59], v[140:143], v[208:211], v[56:59]
	v_mfma_f32_16x16x32_bf16 v[44:47], v[132:135], v[218:221], v[44:47]
	v_mfma_f32_16x16x32_bf16 v[40:43], v[140:143], v[218:221], v[40:43]
	v_mfma_f32_16x16x32_bf16 v[28:31], v[132:135], v[226:229], v[28:31]
	v_mfma_f32_16x16x32_bf16 v[24:27], v[140:143], v[226:229], v[24:27]
	v_mfma_f32_16x16x32_bf16 v[12:15], v[132:135], v[234:237], v[12:15]
	v_mfma_f32_16x16x32_bf16 v[8:11], v[140:143], v[234:237], v[8:11]
	s_setprio 0
	s_setprio 1
	v_mfma_f32_16x16x32_bf16 v[52:55], v[144:147], v[180:183], v[52:55]
	s_add_u32 s0, s0, 0x100
	s_addc_u32 s1, s1, 0
	v_mfma_f32_16x16x32_bf16 v[48:51], v[172:175], v[180:183], v[48:51]
	s_add_u32 s13, s13, 0x100
	s_addc_u32 s22, s22, 0
	v_mfma_f32_16x16x32_bf16 v[36:39], v[144:147], v[214:217], v[36:39]
	s_mov_b32 s18, s23
	s_add_i32 s23, s18, 2
	v_mfma_f32_16x16x32_bf16 v[32:35], v[172:175], v[214:217], v[32:35]
	s_add_u32 s26, s0, 0x80
	s_addc_u32 s19, s1, 0
	v_mfma_f32_16x16x32_bf16 v[20:23], v[144:147], v[222:225], v[20:23]
	s_add_i32 s28, 0, 0x10000
	s_cmp_eq_u32 s25, s18
	v_mfma_f32_16x16x32_bf16 v[16:19], v[172:175], v[222:225], v[16:19]
	s_cselect_b32 s19, s47, s19
	s_cselect_b32 s18, s46, s26
	v_mfma_f32_16x16x32_bf16 v[4:7], v[144:147], v[230:233], v[4:7]
	s_cselect_b32 s27, s51, s22
	s_cselect_b32 s26, s50, s13
	v_mfma_f32_16x16x32_bf16 v[0:3], v[172:175], v[230:233], v[0:3]
	s_add_i32 s29, 0, 0x14000
	v_mfma_f32_16x16x32_bf16 v[52:55], v[148:151], v[208:211], v[52:55]
	s_add_i32 vcc_lo, s2, 2
	s_cmp_ge_u32 s23, vcc_lo
	v_mfma_f32_16x16x32_bf16 v[48:51], v[176:179], v[208:211], v[48:51]
	v_mfma_f32_16x16x32_bf16 v[36:39], v[148:151], v[218:221], v[36:39]
	v_mfma_f32_16x16x32_bf16 v[32:35], v[176:179], v[218:221], v[32:35]
	v_mfma_f32_16x16x32_bf16 v[20:23], v[148:151], v[226:229], v[20:23]
	v_mfma_f32_16x16x32_bf16 v[16:19], v[176:179], v[226:229], v[16:19]
	v_mfma_f32_16x16x32_bf16 v[4:7], v[148:151], v[234:237], v[4:7]
	v_mfma_f32_16x16x32_bf16 v[0:3], v[176:179], v[234:237], v[0:3]
	s_setprio 0
	s_barrier
	s_cbranch_scc0 .Lk311_head
	s_and_b64 vcc, exec, s[82:83]
	s_cbranch_vccz .LBB0_314
	s_barrier

; #define PG8_STAGE(bufoff, gbase, voff) do { _Pragma("unroll") for (int _i = 0; _i < 2; ++_i) \
;         __builtin_amdgcn_global_load_lds((const unsigned*)((const char*)(gbase) + (voff)[_i]), (LAS unsigned*)(lds + (bufoff) + ldsw + _i * 8192), 16, 0, 0); } while (0)
; #define PG8_LDA(dst, b, h) do { _Pragma("unroll") for (int m = 0; m < 4; ++m) _Pragma("unroll") for (int k = 0; k < 2; ++k) dst[m][k] = *(const LAS bf16x8*)(lds + PG8_SA(b, h) + aoff + m * 2048 + k * 1024); } while (0)
; #define PG8_LDB(dst, b, h) do { _Pragma("unroll") for (int n = 0; n < 2; ++n) _Pragma("unroll") for (int k = 0; k < 2; ++k) dst[n][k] = *(const LAS bf16x8*)(lds + PG8_SB(b, h) + boff + n * 2048 + k * 1024); } while (0)
; #define PG8_MMA(ai, bj, At, Bt) do { __builtin_amdgcn_s_setprio(1); _Pragma("unroll") for (int m = 0; m < 4; ++m) _Pragma("unroll") for (int n = 0; n < 2; ++n) _Pragma("unroll") for (int k = 0; k < 2; ++k) \
;         acc[ai][bj][m][n] = __builtin_amdgcn_mfma_f32_16x16x32_bf16(Bt[n][k], At[m][k], acc[ai][bj][m][n], 0, 0, 0); __builtin_amdgcn_s_setprio(0); } while (0)
; #define PG8_WAIT_V(n) asm volatile("s_waitcnt vmcnt(" #n ")" ::: "memory")
; #define PG8_WAIT_L(n) asm volatile("s_waitcnt lgkmcnt(" #n ")" ::: "memory")
; #define PG8_BAR __builtin_amdgcn_s_barrier()
; #define PG8_SCHED __builtin_amdgcn_sched_barrier(0)
; template <class Epi, bool ALIGN_EPI, bool SP2>
; __device__ __forceinline__ void gemm_phase(LAS unsigned char* lds, const Gemm g, const StaticOrder& S, const Epi& E, const int tid) {
;     ...
;             PG8_LDB(B0, 0, 0); PG8_LDB(B1, 0, 1); PG8_SCHED; PG8_LDA(At, 0, 0); PG8_STAGE(PG8_SA(1, 1), a1 + hstep, voffA);
;             PG8_WAIT_V(8); PG8_WAIT_L(0); PG8_BAR; PG8_MMA(0, 0, At, B0); PG8_MMA(0, 1, At, B1); PG8_BAR; PG8_SCHED;
;             PG8_LDA(At, 0, 1); PG8_STAGE(PG8_SB(0, 0), b2, voffB); PG8_STAGE(PG8_SB(0, 1), b2 + hstep, voffB); PG8_STAGE(PG8_SA(0, 0), a2, voffA);
;             PG8_WAIT_V(8); PG8_WAIT_L(0); PG8_BAR; PG8_MMA(1, 0, At, B0); PG8_MMA(1, 1, At, B1); PG8_BAR; PG8_SCHED;
.Lk346_head:
	v_add_u32_e32 v140, s31, v193
	v_add_u32_e32 v156, s27, v193
	ds_read_b128 v[120:123], v140
	ds_read_b128 v[132:135], v140 offset:1024
	ds_read_b128 v[136:139], v140 offset:2048
	ds_read_b128 v[140:143], v140 offset:3072
	ds_read_b128 v[144:147], v156
	ds_read_b128 v[148:151], v156 offset:1024
	ds_read_b128 v[152:155], v156 offset:2048
	ds_read_b128 v[156:159], v156 offset:3072
	v_lshl_add_u64 v[190:191], s[18:19], 0, v[170:171]
	s_add_i32 m0, s15, 0xc000
	ds_read_b128 v[174:177], v208
	ds_read_b128 v[178:181], v208 offset:1024
	ds_read_b128 v[182:185], v208 offset:2048
	ds_read_b128 v[186:189], v208 offset:3072
	ds_read_b128 v[214:217], v208 offset:4096
	ds_read_b128 v[218:221], v208 offset:5120
	ds_read_b128 v[222:225], v208 offset:6144
	ds_read_b128 v[226:229], v208 offset:7168
	global_load_lds_dwordx4 v[190:191], off
	v_lshl_add_u64 v[190:191], s[18:19], 0, v[172:173]
	s_add_i32 m0, s15, 0xe000
	s_nop 0
	global_load_lds_dwordx4 v[190:191], off
	s_waitcnt vmcnt(8)
	s_waitcnt lgkmcnt(0)
	s_barrier
	s_setprio 1
	s_waitcnt lgkmcnt(0)
	v_mfma_f32_16x16x32_bf16 v[128:131], v[120:123], v[174:177], v[128:131]
	v_mfma_f32_16x16x32_bf16 v[124:127], v[136:139], v[174:177], v[124:127]
	v_mfma_f32_16x16x32_bf16 v[108:111], v[120:123], v[182:185], v[108:111]
	v_mfma_f32_16x16x32_bf16 v[104:107], v[136:139], v[182:185], v[104:107]
	v_mfma_f32_16x16x32_bf16 v[92:95], v[120:123], v[214:217], v[92:95]
	v_mfma_f32_16x16x32_bf16 v[88:91], v[136:139], v[214:217], v[88:91]
	v_mfma_f32_16x16x32_bf16 v[76:79], v[120:123], v[222:225], v[76:79]
	v_mfma_f32_16x16x32_bf16 v[72:75], v[136:139], v[222:225], v[72:75]
	v_mfma_f32_16x16x32_bf16 v[128:131], v[132:135], v[178:181], v[128:131]
	v_mfma_f32_16x16x32_bf16 v[124:127], v[140:143], v[178:181], v[124:127]
	v_mfma_f32_16x16x32_bf16 v[108:111], v[132:135], v[186:189], v[108:111]
	v_mfma_f32_16x16x32_bf16 v[104:107], v[140:143], v[186:189], v[104:107]
	v_mfma_f32_16x16x32_bf16 v[92:95], v[132:135], v[218:221], v[92:95]
	v_mfma_f32_16x16x32_bf16 v[88:91], v[140:143], v[218:221], v[88:91]
	v_mfma_f32_16x16x32_bf16 v[76:79], v[132:135], v[226:229], v[76:79]
	v_mfma_f32_16x16x32_bf16 v[72:75], v[140:143], v[226:229], v[72:75]
	s_setprio 0
	s_setprio 1
	v_mfma_f32_16x16x32_bf16 v[116:119], v[144:147], v[174:177], v[116:119]
	v_mfma_f32_16x16x32_bf16 v[112:115], v[152:155], v[174:177], v[112:115]
	v_mfma_f32_16x16x32_bf16 v[100:103], v[144:147], v[182:185], v[100:103]
	v_mfma_f32_16x16x32_bf16 v[96:99], v[152:155], v[182:185], v[96:99]
	v_mfma_f32_16x16x32_bf16 v[84:87], v[144:147], v[214:217], v[84:87]
	v_mfma_f32_16x16x32_bf16 v[80:83], v[152:155], v[214:217], v[80:83]
	v_mfma_f32_16x16x32_bf16 v[68:71], v[144:147], v[222:225], v[68:71]
	v_mfma_f32_16x16x32_bf16 v[64:67], v[152:155], v[222:225], v[64:67]
	v_mfma_f32_16x16x32_bf16 v[116:119], v[148:151], v[178:181], v[116:119]
	v_mfma_f32_16x16x32_bf16 v[112:115], v[156:159], v[178:181], v[112:115]
	v_mfma_f32_16x16x32_bf16 v[100:103], v[148:151], v[186:189], v[100:103]
	v_mfma_f32_16x16x32_bf16 v[96:99], v[156:159], v[186:189], v[96:99]
	v_mfma_f32_16x16x32_bf16 v[84:87], v[148:151], v[218:221], v[84:87]
	v_mfma_f32_16x16x32_bf16 v[80:83], v[156:159], v[218:221], v[80:83]
	v_mfma_f32_16x16x32_bf16 v[68:71], v[148:151], v[226:229], v[68:71]
	v_mfma_f32_16x16x32_bf16 v[64:67], v[156:159], v[226:229], v[64:67]
	s_setprio 0
	s_barrier
	s_add_i32 s31, s31, s14
	v_lshl_add_u64 v[190:191], s[34:35], 0, v[160:161]
	s_mov_b32 m0, s31
	ds_read_b128 v[174:177], v208 offset:16384
	ds_read_b128 v[178:181], v208 offset:17408
	ds_read_b128 v[182:185], v208 offset:18432
	ds_read_b128 v[186:189], v208 offset:19456
	ds_read_b128 v[214:217], v208 offset:20480
	ds_read_b128 v[218:221], v208 offset:21504
	ds_read_b128 v[222:225], v208 offset:22528
	ds_read_b128 v[226:229], v208 offset:23552
	global_load_lds_dwordx4 v[190:191], off
	s_add_i32 m0, s31, 0x2000
	v_lshl_add_u64 v[210:211], s[34:35], 0, v[168:169]
	s_add_u32 s34, s34, s44
	s_addc_u32 s35, s35, 0
	s_add_i32 s27, s27, s14
	global_load_lds_dwordx4 v[210:211], off
	v_lshl_add_u64 v[230:231], s[34:35], 0, v[160:161]
	s_mov_b32 m0, s27
	v_lshl_add_u64 v[232:233], s[34:35], 0, v[168:169]
	global_load_lds_dwordx4 v[230:231], off
	s_add_i32 m0, s27, 0x2000
	v_lshl_add_u64 v[234:235], s[28:29], 0, v[160:161]
	global_load_lds_dwordx4 v[232:233], off
	s_mov_b32 m0, s15
	v_lshl_add_u64 v[236:237], s[28:29], 0, v[168:169]
	global_load_lds_dwordx4 v[234:235], off
	s_mov_b32 m0, s25
	s_nop 0
	global_load_lds_dwordx4 v[236:237], off
	s_waitcnt vmcnt(8)
	s_waitcnt lgkmcnt(0)
	s_barrier
; #define PG8_STAGE(bufoff, gbase, voff) do { _Pragma("unroll") for (int _i = 0; _i < 2; ++_i) \
;         __builtin_amdgcn_global_load_lds((const unsigned*)((const char*)(gbase) + (voff)[_i]), (LAS unsigned*)(lds + (bufoff) + ldsw + _i * 8192), 16, 0, 0); } while (0)
; #define PG8_LDA(dst, b, h) do { _Pragma("unroll") for (int m = 0; m < 4; ++m) _Pragma("unroll") for (int k = 0; k < 2; ++k) dst[m][k] = *(const LAS bf16x8*)(lds + PG8_SA(b, h) + aoff + m * 2048 + k * 1024); } while (0)
; #define PG8_LDB(dst, b, h) do { _Pragma("unroll") for (int n = 0; n < 2; ++n) _Pragma("unroll") for (int k = 0; k < 2; ++k) dst[n][k] = *(const LAS bf16x8*)(lds + PG8_SB(b, h) + boff + n * 2048 + k * 1024); } while (0)
; #define PG8_MMA(ai, bj, At, Bt) do { __builtin_amdgcn_s_setprio(1); _Pragma("unroll") for (int m = 0; m < 4; ++m) _Pragma("unroll") for (int n = 0; n < 2; ++n) _Pragma("unroll") for (int k = 0; k < 2; ++k) \
;         acc[ai][bj][m][n] = __builtin_amdgcn_mfma_f32_16x16x32_bf16(Bt[n][k], At[m][k], acc[ai][bj][m][n], 0, 0, 0); __builtin_amdgcn_s_setprio(0); } while (0)
; #define PG8_WAIT_V(n) asm volatile("s_waitcnt vmcnt(" #n ")" ::: "memory")
; #define PG8_WAIT_L(n) asm volatile("s_waitcnt lgkmcnt(" #n ")" ::: "memory")
; #define PG8_BAR __builtin_amdgcn_s_barrier()
; #define PG8_SCHED __builtin_amdgcn_sched_barrier(0)
; template <class Epi, bool ALIGN_EPI, bool SP2>
; __device__ __forceinline__ void gemm_phase(LAS unsigned char* lds, const Gemm g, const StaticOrder& S, const Epi& E, const int tid) {
;     ...
;             PG8_LDA(At, 0, 1); PG8_STAGE(PG8_SB(0, 0), b2, voffB); PG8_STAGE(PG8_SB(0, 1), b2 + hstep, voffB); PG8_STAGE(PG8_SA(0, 0), a2, voffA);
;             PG8_WAIT_V(8); PG8_WAIT_L(0); PG8_BAR; PG8_MMA(1, 0, At, B0); PG8_MMA(1, 1, At, B1); PG8_BAR; PG8_SCHED;
;             PG8_LDB(B0, 1, 0); PG8_LDB(B1, 1, 1); PG8_SCHED; PG8_LDA(At, 1, 0); PG8_STAGE(PG8_SA(0, 1), a2 + hstep, voffA);
;             PG8_WAIT_V(8); PG8_WAIT_L(0); PG8_BAR; PG8_MMA(0, 0, At, B0); PG8_MMA(0, 1, At, B1); PG8_BAR; PG8_SCHED;
;             PG8_LDA(At, 1, 1); PG8_STAGE(PG8_SB(1, 0), b3, voffB); PG8_STAGE(PG8_SB(1, 1), b3 + hstep, voffB); PG8_STAGE(PG8_SA(1, 0), a3, voffA);
	s_setprio 1
	s_waitcnt lgkmcnt(0)
	v_mfma_f32_16x16x32_bf16 v[60:63], v[120:123], v[174:177], v[60:63]
	v_mfma_f32_16x16x32_bf16 v[56:59], v[136:139], v[174:177], v[56:59]
	v_mfma_f32_16x16x32_bf16 v[44:47], v[120:123], v[182:185], v[44:47]
	v_mfma_f32_16x16x32_bf16 v[40:43], v[136:139], v[182:185], v[40:43]
	v_mfma_f32_16x16x32_bf16 v[28:31], v[120:123], v[214:217], v[28:31]
	v_mfma_f32_16x16x32_bf16 v[24:27], v[136:139], v[214:217], v[24:27]
	v_mfma_f32_16x16x32_bf16 v[12:15], v[120:123], v[222:225], v[12:15]
	v_mfma_f32_16x16x32_bf16 v[8:11], v[136:139], v[222:225], v[8:11]
	v_mfma_f32_16x16x32_bf16 v[60:63], v[132:135], v[178:181], v[60:63]
	v_mfma_f32_16x16x32_bf16 v[56:59], v[140:143], v[178:181], v[56:59]
	v_mfma_f32_16x16x32_bf16 v[44:47], v[132:135], v[186:189], v[44:47]
	v_mfma_f32_16x16x32_bf16 v[40:43], v[140:143], v[186:189], v[40:43]
	v_mfma_f32_16x16x32_bf16 v[28:31], v[132:135], v[218:221], v[28:31]
	v_mfma_f32_16x16x32_bf16 v[24:27], v[140:143], v[218:221], v[24:27]
	v_mfma_f32_16x16x32_bf16 v[12:15], v[132:135], v[226:229], v[12:15]
	v_mfma_f32_16x16x32_bf16 v[8:11], v[140:143], v[226:229], v[8:11]
	s_setprio 0
	s_setprio 1
	v_mfma_f32_16x16x32_bf16 v[52:55], v[144:147], v[174:177], v[52:55]
	v_mfma_f32_16x16x32_bf16 v[48:51], v[152:155], v[174:177], v[48:51]
	v_mfma_f32_16x16x32_bf16 v[36:39], v[144:147], v[182:185], v[36:39]
	v_mfma_f32_16x16x32_bf16 v[32:35], v[152:155], v[182:185], v[32:35]
	v_mfma_f32_16x16x32_bf16 v[20:23], v[144:147], v[214:217], v[20:23]
	v_mfma_f32_16x16x32_bf16 v[16:19], v[152:155], v[214:217], v[16:19]
	v_mfma_f32_16x16x32_bf16 v[4:7], v[144:147], v[222:225], v[4:7]
	v_mfma_f32_16x16x32_bf16 v[0:3], v[152:155], v[222:225], v[0:3]
	v_mfma_f32_16x16x32_bf16 v[52:55], v[148:151], v[178:181], v[52:55]
	v_mfma_f32_16x16x32_bf16 v[48:51], v[156:159], v[178:181], v[48:51]
	v_mfma_f32_16x16x32_bf16 v[36:39], v[148:151], v[186:189], v[36:39]
	v_mfma_f32_16x16x32_bf16 v[32:35], v[156:159], v[186:189], v[32:35]
	v_mfma_f32_16x16x32_bf16 v[20:23], v[148:151], v[218:221], v[20:23]
	v_mfma_f32_16x16x32_bf16 v[16:19], v[156:159], v[218:221], v[16:19]
	v_mfma_f32_16x16x32_bf16 v[4:7], v[148:151], v[226:229], v[4:7]
	v_mfma_f32_16x16x32_bf16 v[0:3], v[156:159], v[226:229], v[0:3]
	s_setprio 0
	s_barrier
	s_add_i32 s27, 0, 0x18000
	s_add_i32 s31, 0, 0x1c000
	v_add_u32_e32 v140, s27, v193
	v_add_u32_e32 v156, s31, v193
	ds_read_b128 v[120:123], v140
	ds_read_b128 v[132:135], v140 offset:1024
	ds_read_b128 v[136:139], v140 offset:2048
	ds_read_b128 v[140:143], v140 offset:3072
	ds_read_b128 v[144:147], v156
	ds_read_b128 v[148:151], v156 offset:1024
	ds_read_b128 v[152:155], v156 offset:2048
	ds_read_b128 v[156:159], v156 offset:3072
	s_add_u32 s28, s28, s44
	s_addc_u32 s29, s29, 0
	s_mov_b32 m0, s54
	v_lshl_add_u64 v[238:239], s[28:29], 0, v[160:161]
	ds_read_b128 v[174:177], v208 offset:32768
	ds_read_b128 v[178:181], v208 offset:33792
	ds_read_b128 v[182:185], v208 offset:34816
	ds_read_b128 v[186:189], v208 offset:35840
	ds_read_b128 v[214:217], v208 offset:36864
	ds_read_b128 v[218:221], v208 offset:37888
	ds_read_b128 v[222:225], v208 offset:38912
	ds_read_b128 v[226:229], v208 offset:39936
	global_load_lds_dwordx4 v[238:239], off
	v_lshl_add_u64 v[238:239], s[28:29], 0, v[168:169]
	s_mov_b32 m0, s55
	s_nop 0
	global_load_lds_dwordx4 v[238:239], off
	s_waitcnt vmcnt(8)
	s_waitcnt lgkmcnt(0)
	s_barrier
	s_setprio 1
	s_waitcnt lgkmcnt(0)
	v_mfma_f32_16x16x32_bf16 v[128:131], v[120:123], v[174:177], v[128:131]
	v_mfma_f32_16x16x32_bf16 v[124:127], v[136:139], v[174:177], v[124:127]
	v_mfma_f32_16x16x32_bf16 v[108:111], v[120:123], v[182:185], v[108:111]
	v_mfma_f32_16x16x32_bf16 v[104:107], v[136:139], v[182:185], v[104:107]
	v_mfma_f32_16x16x32_bf16 v[92:95], v[120:123], v[214:217], v[92:95]
	v_mfma_f32_16x16x32_bf16 v[88:91], v[136:139], v[214:217], v[88:91]
	v_mfma_f32_16x16x32_bf16 v[76:79], v[120:123], v[222:225], v[76:79]
	v_mfma_f32_16x16x32_bf16 v[72:75], v[136:139], v[222:225], v[72:75]
	v_mfma_f32_16x16x32_bf16 v[128:131], v[132:135], v[178:181], v[128:131]
	v_mfma_f32_16x16x32_bf16 v[124:127], v[140:143], v[178:181], v[124:127]
	v_mfma_f32_16x16x32_bf16 v[108:111], v[132:135], v[186:189], v[108:111]
	v_mfma_f32_16x16x32_bf16 v[104:107], v[140:143], v[186:189], v[104:107]
	v_mfma_f32_16x16x32_bf16 v[92:95], v[132:135], v[218:221], v[92:95]
	v_mfma_f32_16x16x32_bf16 v[88:91], v[140:143], v[218:221], v[88:91]
	v_mfma_f32_16x16x32_bf16 v[76:79], v[132:135], v[226:229], v[76:79]
	v_mfma_f32_16x16x32_bf16 v[72:75], v[140:143], v[226:229], v[72:75]
	s_setprio 0
	s_setprio 1
	v_mfma_f32_16x16x32_bf16 v[116:119], v[144:147], v[174:177], v[116:119]
	v_mfma_f32_16x16x32_bf16 v[112:115], v[152:155], v[174:177], v[112:115]
	v_mfma_f32_16x16x32_bf16 v[100:103], v[144:147], v[182:185], v[100:103]
	v_mfma_f32_16x16x32_bf16 v[96:99], v[152:155], v[182:185], v[96:99]
	v_mfma_f32_16x16x32_bf16 v[84:87], v[144:147], v[214:217], v[84:87]
	v_mfma_f32_16x16x32_bf16 v[80:83], v[152:155], v[214:217], v[80:83]
	v_mfma_f32_16x16x32_bf16 v[68:71], v[144:147], v[222:225], v[68:71]
	v_mfma_f32_16x16x32_bf16 v[64:67], v[152:155], v[222:225], v[64:67]
	v_mfma_f32_16x16x32_bf16 v[116:119], v[148:151], v[178:181], v[116:119]
	v_mfma_f32_16x16x32_bf16 v[112:115], v[156:159], v[178:181], v[112:115]
	v_mfma_f32_16x16x32_bf16 v[100:103], v[148:151], v[186:189], v[100:103]
	v_mfma_f32_16x16x32_bf16 v[96:99], v[156:159], v[186:189], v[96:99]
	v_mfma_f32_16x16x32_bf16 v[84:87], v[148:151], v[218:221], v[84:87]
	v_mfma_f32_16x16x32_bf16 v[80:83], v[156:159], v[218:221], v[80:83]
	v_mfma_f32_16x16x32_bf16 v[68:71], v[148:151], v[226:229], v[68:71]
	v_mfma_f32_16x16x32_bf16 v[64:67], v[156:159], v[226:229], v[64:67]
	s_setprio 0
	s_barrier
; #define PG8_STAGE(bufoff, gbase, voff) do { _Pragma("unroll") for (int _i = 0; _i < 2; ++_i) \
;         __builtin_amdgcn_global_load_lds((const unsigned*)((const char*)(gbase) + (voff)[_i]), (LAS unsigned*)(lds + (bufoff) + ldsw + _i * 8192), 16, 0, 0); } while (0)
; #define PG8_LDA(dst, b, h) do { _Pragma("unroll") for (int m = 0; m < 4; ++m) _Pragma("unroll") for (int k = 0; k < 2; ++k) dst[m][k] = *(const LAS bf16x8*)(lds + PG8_SA(b, h) + aoff + m * 2048 + k * 1024); } while (0)
; #define PG8_MMA(ai, bj, At, Bt) do { __builtin_amdgcn_s_setprio(1); _Pragma("unroll") for (int m = 0; m < 4; ++m) _Pragma("unroll") for (int n = 0; n < 2; ++n) _Pragma("unroll") for (int k = 0; k < 2; ++k) \
;         acc[ai][bj][m][n] = __builtin_amdgcn_mfma_f32_16x16x32_bf16(Bt[n][k], At[m][k], acc[ai][bj][m][n], 0, 0, 0); __builtin_amdgcn_s_setprio(0); } while (0)
; #define PG8_WAIT_V(n) asm volatile("s_waitcnt vmcnt(" #n ")" ::: "memory")
; #define PG8_WAIT_L(n) asm volatile("s_waitcnt lgkmcnt(" #n ")" ::: "memory")
; #define PG8_BAR __builtin_amdgcn_s_barrier()
; #define PG8_SCHED __builtin_amdgcn_sched_barrier(0)
; template <class Epi, bool ALIGN_EPI, bool SP2>
; __device__ __forceinline__ void gemm_phase(LAS unsigned char* lds, const Gemm g, const StaticOrder& S, const Epi& E, const int tid) {
;     ...
;         for (int t = 0; t < nt; t += 2) {
;             const bool last = (t == nt - 2);
;             const char* a1 = cA + (size_t)(t + 1) * kstep;
;             const char* a2 = last ? nA : cA + (size_t)(t + 2) * kstep; const char* b2 = last ? nB : cB + (size_t)(t + 2) * kstep;
;             const char* a3 = a2 + kstep; const char* b3 = b2 + kstep;
;     ...
;             PG8_LDA(At, 1, 1); PG8_STAGE(PG8_SB(1, 0), b3, voffB); PG8_STAGE(PG8_SB(1, 1), b3 + hstep, voffB); PG8_STAGE(PG8_SA(1, 0), a3, voffA);
;             PG8_WAIT_V(8); PG8_WAIT_L(0); PG8_BAR; PG8_MMA(1, 0, At, B0); PG8_MMA(1, 1, At, B1); PG8_BAR; PG8_SCHED;
	s_add_i32 s27, s27, s14
	v_lshl_add_u64 v[190:191], v[190:191], 0, s[8:9]
	s_mov_b32 m0, s27
	ds_read_b128 v[174:177], v208 offset:49152
	ds_read_b128 v[178:181], v208 offset:50176
	ds_read_b128 v[182:185], v208 offset:51200
	ds_read_b128 v[186:189], v208 offset:52224
	ds_read_b128 v[214:217], v208 offset:53248
	ds_read_b128 v[218:221], v208 offset:54272
	ds_read_b128 v[222:225], v208 offset:55296
	ds_read_b128 v[226:229], v208 offset:56320
	global_load_lds_dwordx4 v[190:191], off
	v_lshl_add_u64 v[190:191], v[210:211], 0, s[8:9]
	s_add_i32 m0, s27, 0x2000
	s_add_i32 s27, s31, s14
	global_load_lds_dwordx4 v[190:191], off
	v_lshl_add_u64 v[190:191], v[230:231], 0, s[8:9]
	s_mov_b32 m0, s27
	s_nop 0
	global_load_lds_dwordx4 v[190:191], off
	v_lshl_add_u64 v[190:191], v[232:233], 0, s[8:9]
	s_add_i32 m0, s27, 0x2000
	s_nop 0
	global_load_lds_dwordx4 v[190:191], off
	v_lshl_add_u64 v[190:191], v[234:235], 0, s[8:9]
	s_mov_b32 m0, s46
	s_nop 0
	global_load_lds_dwordx4 v[190:191], off
	v_lshl_add_u64 v[190:191], v[236:237], 0, s[8:9]
	s_mov_b32 m0, s47
	s_nop 0
	global_load_lds_dwordx4 v[190:191], off
	s_waitcnt vmcnt(8)
	s_waitcnt lgkmcnt(0)
	s_barrier
	s_setprio 1
	s_waitcnt lgkmcnt(0)
	v_mfma_f32_16x16x32_bf16 v[60:63], v[120:123], v[174:177], v[60:63]
	v_mfma_f32_16x16x32_bf16 v[56:59], v[136:139], v[174:177], v[56:59]
	v_mfma_f32_16x16x32_bf16 v[44:47], v[120:123], v[182:185], v[44:47]
	v_mfma_f32_16x16x32_bf16 v[40:43], v[136:139], v[182:185], v[40:43]
	v_mfma_f32_16x16x32_bf16 v[28:31], v[120:123], v[214:217], v[28:31]
	v_mfma_f32_16x16x32_bf16 v[24:27], v[136:139], v[214:217], v[24:27]
	v_mfma_f32_16x16x32_bf16 v[12:15], v[120:123], v[222:225], v[12:15]
	v_mfma_f32_16x16x32_bf16 v[8:11], v[136:139], v[222:225], v[8:11]
	v_mfma_f32_16x16x32_bf16 v[60:63], v[132:135], v[178:181], v[60:63]
	v_mfma_f32_16x16x32_bf16 v[56:59], v[140:143], v[178:181], v[56:59]
	v_mfma_f32_16x16x32_bf16 v[44:47], v[132:135], v[186:189], v[44:47]
	v_mfma_f32_16x16x32_bf16 v[40:43], v[140:143], v[186:189], v[40:43]
	v_mfma_f32_16x16x32_bf16 v[28:31], v[132:135], v[218:221], v[28:31]
	v_mfma_f32_16x16x32_bf16 v[24:27], v[140:143], v[218:221], v[24:27]
	v_mfma_f32_16x16x32_bf16 v[12:15], v[132:135], v[226:229], v[12:15]
	v_mfma_f32_16x16x32_bf16 v[8:11], v[140:143], v[226:229], v[8:11]
	s_setprio 0
	s_setprio 1
	v_mfma_f32_16x16x32_bf16 v[52:55], v[144:147], v[174:177], v[52:55]
	s_add_u32 s18, s18, 0x100
	s_addc_u32 s19, s19, 0
	v_mfma_f32_16x16x32_bf16 v[48:51], v[152:155], v[174:177], v[48:51]
	s_add_u32 s13, s13, 0x100
	s_addc_u32 s26, s26, 0
	v_mfma_f32_16x16x32_bf16 v[36:39], v[144:147], v[182:185], v[36:39]
	s_mov_b32 s27, s30
	s_add_i32 s30, s27, 2
	v_mfma_f32_16x16x32_bf16 v[32:35], v[152:155], v[182:185], v[32:35]
	s_add_u32 s28, s18, 0x80
	s_addc_u32 s29, s19, 0
	v_mfma_f32_16x16x32_bf16 v[20:23], v[144:147], v[214:217], v[20:23]
	s_add_i32 s31, 0, 0x10000
	s_cmp_eq_u32 s97, s27
	v_mfma_f32_16x16x32_bf16 v[16:19], v[152:155], v[214:217], v[16:19]
	s_cselect_b32 s29, s1, s29
	s_cselect_b32 s28, s0, s28
	v_mfma_f32_16x16x32_bf16 v[4:7], v[144:147], v[222:225], v[4:7]
	s_cselect_b32 s35, s43, s26
	s_cselect_b32 s34, s42, s13
	v_mfma_f32_16x16x32_bf16 v[0:3], v[152:155], v[222:225], v[0:3]
	s_add_i32 s27, 0, 0x14000
	v_mfma_f32_16x16x32_bf16 v[52:55], v[148:151], v[178:181], v[52:55]
	s_add_i32 vcc_lo, s52, 2
	s_cmp_ge_u32 s30, vcc_lo
	v_mfma_f32_16x16x32_bf16 v[48:51], v[156:159], v[178:181], v[48:51]
	v_mfma_f32_16x16x32_bf16 v[36:39], v[148:151], v[186:189], v[36:39]
	v_mfma_f32_16x16x32_bf16 v[32:35], v[156:159], v[186:189], v[32:35]
	v_mfma_f32_16x16x32_bf16 v[20:23], v[148:151], v[218:221], v[20:23]
	v_mfma_f32_16x16x32_bf16 v[16:19], v[156:159], v[218:221], v[16:19]
	v_mfma_f32_16x16x32_bf16 v[4:7], v[148:151], v[226:229], v[4:7]
	v_mfma_f32_16x16x32_bf16 v[0:3], v[156:159], v[226:229], v[0:3]
	s_setprio 0
	s_barrier
	s_cbranch_scc0 .Lk346_head
	s_and_b64 vcc, exec, s[64:65]
	s_cbranch_vccz .LBB0_349
	s_barrier

; #define PG8_STAGE(bufoff, gbase, voff) do { _Pragma("unroll") for (int _i = 0; _i < 2; ++_i) \
;         __builtin_amdgcn_global_load_lds((const unsigned*)((const char*)(gbase) + (voff)[_i]), (LAS unsigned*)(lds + (bufoff) + ldsw + _i * 8192), 16, 0, 0); } while (0)
; #define PG8_LDA(dst, b, h) do { _Pragma("unroll") for (int m = 0; m < 4; ++m) _Pragma("unroll") for (int k = 0; k < 2; ++k) dst[m][k] = *(const LAS bf16x8*)(lds + PG8_SA(b, h) + aoff + m * 2048 + k * 1024); } while (0)
; #define PG8_LDB(dst, b, h) do { _Pragma("unroll") for (int n = 0; n < 2; ++n) _Pragma("unroll") for (int k = 0; k < 2; ++k) dst[n][k] = *(const LAS bf16x8*)(lds + PG8_SB(b, h) + boff + n * 2048 + k * 1024); } while (0)
; #define PG8_MMA(ai, bj, At, Bt) do { __builtin_amdgcn_s_setprio(1); _Pragma("unroll") for (int m = 0; m < 4; ++m) _Pragma("unroll") for (int n = 0; n < 2; ++n) _Pragma("unroll") for (int k = 0; k < 2; ++k) \
;         acc[ai][bj][m][n] = __builtin_amdgcn_mfma_f32_16x16x32_bf16(Bt[n][k], At[m][k], acc[ai][bj][m][n], 0, 0, 0); __builtin_amdgcn_s_setprio(0); } while (0)
; #define PG8_WAIT_V(n) asm volatile("s_waitcnt vmcnt(" #n ")" ::: "memory")
; #define PG8_WAIT_L(n) asm volatile("s_waitcnt lgkmcnt(" #n ")" ::: "memory")
; #define PG8_BAR __builtin_amdgcn_s_barrier()
; #define PG8_SCHED __builtin_amdgcn_sched_barrier(0)
; template <class Epi, bool ALIGN_EPI, bool SP2>
; __device__ __forceinline__ void gemm_phase(LAS unsigned char* lds, const Gemm g, const StaticOrder& S, const Epi& E, const int tid) {
;     ...
;             PG8_LDB(B0, 0, 0); PG8_LDB(B1, 0, 1); PG8_SCHED; PG8_LDA(At, 0, 0); PG8_STAGE(PG8_SA(1, 1), a1 + hstep, voffA);
;             PG8_WAIT_V(8); PG8_WAIT_L(0); PG8_BAR; PG8_MMA(0, 0, At, B0); PG8_MMA(0, 1, At, B1); PG8_BAR; PG8_SCHED;
;             PG8_LDA(At, 0, 1); PG8_STAGE(PG8_SB(0, 0), b2, voffB); PG8_STAGE(PG8_SB(0, 1), b2 + hstep, voffB); PG8_STAGE(PG8_SA(0, 0), a2, voffA);
;             PG8_WAIT_V(8); PG8_WAIT_L(0); PG8_BAR; PG8_MMA(1, 0, At, B0); PG8_MMA(1, 1, At, B1); PG8_BAR; PG8_SCHED;
.Lk398_head:
	v_add_u32_e32 v140, s42, v167
	v_add_u32_e32 v172, s43, v167
	ds_read_b128 v[104:107], v140
	ds_read_b128 v[132:135], v140 offset:1024
	ds_read_b128 v[136:139], v140 offset:2048
	ds_read_b128 v[140:143], v140 offset:3072
	ds_read_b128 v[144:147], v172
	ds_read_b128 v[156:159], v172 offset:1024
	ds_read_b128 v[168:171], v172 offset:2048
	ds_read_b128 v[172:175], v172 offset:3072
	v_lshl_add_u64 v[180:181], s[0:1], 0, v[152:153]
	s_add_i32 m0, s15, 0xc000
	ds_read_b128 v[176:179], v183
	ds_read_b128 v[184:187], v183 offset:1024
	ds_read_b128 v[188:191], v183 offset:2048
	ds_read_b128 v[208:211], v183 offset:3072
	ds_read_b128 v[214:217], v183 offset:4096
	ds_read_b128 v[218:221], v183 offset:5120
	ds_read_b128 v[222:225], v183 offset:6144
	ds_read_b128 v[226:229], v183 offset:7168
	global_load_lds_dwordx4 v[180:181], off
	v_lshl_add_u64 v[180:181], s[0:1], 0, v[154:155]
	s_add_i32 m0, s15, 0xe000
	s_nop 0
	global_load_lds_dwordx4 v[180:181], off
	s_waitcnt vmcnt(8)
	s_waitcnt lgkmcnt(0)
	s_barrier
	s_setprio 1
	s_waitcnt lgkmcnt(0)
	v_mfma_f32_16x16x32_bf16 v[128:131], v[104:107], v[176:179], v[128:131]
	v_mfma_f32_16x16x32_bf16 v[124:127], v[136:139], v[176:179], v[124:127]
	v_mfma_f32_16x16x32_bf16 v[112:115], v[104:107], v[188:191], v[112:115]
	v_mfma_f32_16x16x32_bf16 v[108:111], v[136:139], v[188:191], v[108:111]
	v_mfma_f32_16x16x32_bf16 v[92:95], v[104:107], v[214:217], v[92:95]
	v_mfma_f32_16x16x32_bf16 v[88:91], v[136:139], v[214:217], v[88:91]
	v_mfma_f32_16x16x32_bf16 v[76:79], v[104:107], v[222:225], v[76:79]
	v_mfma_f32_16x16x32_bf16 v[72:75], v[136:139], v[222:225], v[72:75]
	v_mfma_f32_16x16x32_bf16 v[128:131], v[132:135], v[184:187], v[128:131]
	v_mfma_f32_16x16x32_bf16 v[124:127], v[140:143], v[184:187], v[124:127]
	v_mfma_f32_16x16x32_bf16 v[112:115], v[132:135], v[208:211], v[112:115]
	v_mfma_f32_16x16x32_bf16 v[108:111], v[140:143], v[208:211], v[108:111]
	v_mfma_f32_16x16x32_bf16 v[92:95], v[132:135], v[218:221], v[92:95]
	v_mfma_f32_16x16x32_bf16 v[88:91], v[140:143], v[218:221], v[88:91]
	v_mfma_f32_16x16x32_bf16 v[76:79], v[132:135], v[226:229], v[76:79]
	v_mfma_f32_16x16x32_bf16 v[72:75], v[140:143], v[226:229], v[72:75]
	s_setprio 0
	s_setprio 1
	v_mfma_f32_16x16x32_bf16 v[120:123], v[144:147], v[176:179], v[120:123]
	v_mfma_f32_16x16x32_bf16 v[116:119], v[168:171], v[176:179], v[116:119]
	v_mfma_f32_16x16x32_bf16 v[100:103], v[144:147], v[188:191], v[100:103]
	v_mfma_f32_16x16x32_bf16 v[96:99], v[168:171], v[188:191], v[96:99]
	v_mfma_f32_16x16x32_bf16 v[84:87], v[144:147], v[214:217], v[84:87]
	v_mfma_f32_16x16x32_bf16 v[80:83], v[168:171], v[214:217], v[80:83]
	v_mfma_f32_16x16x32_bf16 v[68:71], v[144:147], v[222:225], v[68:71]
	v_mfma_f32_16x16x32_bf16 v[64:67], v[168:171], v[222:225], v[64:67]
	v_mfma_f32_16x16x32_bf16 v[120:123], v[156:159], v[184:187], v[120:123]
	v_mfma_f32_16x16x32_bf16 v[116:119], v[172:175], v[184:187], v[116:119]
	v_mfma_f32_16x16x32_bf16 v[100:103], v[156:159], v[208:211], v[100:103]
	v_mfma_f32_16x16x32_bf16 v[96:99], v[172:175], v[208:211], v[96:99]
	v_mfma_f32_16x16x32_bf16 v[84:87], v[156:159], v[218:221], v[84:87]
	v_mfma_f32_16x16x32_bf16 v[80:83], v[172:175], v[218:221], v[80:83]
	v_mfma_f32_16x16x32_bf16 v[68:71], v[156:159], v[226:229], v[68:71]
	v_mfma_f32_16x16x32_bf16 v[64:67], v[172:175], v[226:229], v[64:67]
	s_setprio 0
	s_barrier
	s_add_i32 s42, s42, s14
	v_lshl_add_u64 v[180:181], s[40:41], 0, v[148:149]
	s_mov_b32 m0, s42
	ds_read_b128 v[176:179], v183 offset:16384
	ds_read_b128 v[184:187], v183 offset:17408
	ds_read_b128 v[188:191], v183 offset:18432
	ds_read_b128 v[208:211], v183 offset:19456
	ds_read_b128 v[214:217], v183 offset:20480
	ds_read_b128 v[218:221], v183 offset:21504
	ds_read_b128 v[222:225], v183 offset:22528
	ds_read_b128 v[226:229], v183 offset:23552
	global_load_lds_dwordx4 v[180:181], off
	s_add_i32 m0, s42, 0x2000
	v_lshl_add_u64 v[192:193], s[40:41], 0, v[150:151]
	s_add_u32 s40, s40, s44
	s_addc_u32 s41, s41, 0
	s_add_i32 s42, s43, s14
	global_load_lds_dwordx4 v[192:193], off
	v_lshl_add_u64 v[230:231], s[40:41], 0, v[148:149]
	s_mov_b32 m0, s42
	v_lshl_add_u64 v[232:233], s[40:41], 0, v[150:151]
	global_load_lds_dwordx4 v[230:231], off
	s_add_i32 m0, s42, 0x2000
	v_lshl_add_u64 v[234:235], s[28:29], 0, v[148:149]
	global_load_lds_dwordx4 v[232:233], off
	s_mov_b32 m0, s15
	v_lshl_add_u64 v[236:237], s[28:29], 0, v[150:151]
	global_load_lds_dwordx4 v[234:235], off
	s_mov_b32 m0, s22
	s_nop 0
	global_load_lds_dwordx4 v[236:237], off
	s_waitcnt vmcnt(8)
	s_waitcnt lgkmcnt(0)
	s_barrier
; #define PG8_STAGE(bufoff, gbase, voff) do { _Pragma("unroll") for (int _i = 0; _i < 2; ++_i) \
;         __builtin_amdgcn_global_load_lds((const unsigned*)((const char*)(gbase) + (voff)[_i]), (LAS unsigned*)(lds + (bufoff) + ldsw + _i * 8192), 16, 0, 0); } while (0)
; #define PG8_LDA(dst, b, h) do { _Pragma("unroll") for (int m = 0; m < 4; ++m) _Pragma("unroll") for (int k = 0; k < 2; ++k) dst[m][k] = *(const LAS bf16x8*)(lds + PG8_SA(b, h) + aoff + m * 2048 + k * 1024); } while (0)
; #define PG8_LDB(dst, b, h) do { _Pragma("unroll") for (int n = 0; n < 2; ++n) _Pragma("unroll") for (int k = 0; k < 2; ++k) dst[n][k] = *(const LAS bf16x8*)(lds + PG8_SB(b, h) + boff + n * 2048 + k * 1024); } while (0)
; #define PG8_MMA(ai, bj, At, Bt) do { __builtin_amdgcn_s_setprio(1); _Pragma("unroll") for (int m = 0; m < 4; ++m) _Pragma("unroll") for (int n = 0; n < 2; ++n) _Pragma("unroll") for (int k = 0; k < 2; ++k) \
;         acc[ai][bj][m][n] = __builtin_amdgcn_mfma_f32_16x16x32_bf16(Bt[n][k], At[m][k], acc[ai][bj][m][n], 0, 0, 0); __builtin_amdgcn_s_setprio(0); } while (0)
; #define PG8_WAIT_V(n) asm volatile("s_waitcnt vmcnt(" #n ")" ::: "memory")
; #define PG8_WAIT_L(n) asm volatile("s_waitcnt lgkmcnt(" #n ")" ::: "memory")
; #define PG8_BAR __builtin_amdgcn_s_barrier()
; #define PG8_SCHED __builtin_amdgcn_sched_barrier(0)
; template <class Epi, bool ALIGN_EPI, bool SP2>
; __device__ __forceinline__ void gemm_phase(LAS unsigned char* lds, const Gemm g, const StaticOrder& S, const Epi& E, const int tid) {
;     ...
;             PG8_LDA(At, 0, 1); PG8_STAGE(PG8_SB(0, 0), b2, voffB); PG8_STAGE(PG8_SB(0, 1), b2 + hstep, voffB); PG8_STAGE(PG8_SA(0, 0), a2, voffA);
;             PG8_WAIT_V(8); PG8_WAIT_L(0); PG8_BAR; PG8_MMA(1, 0, At, B0); PG8_MMA(1, 1, At, B1); PG8_BAR; PG8_SCHED;
;             PG8_LDB(B0, 1, 0); PG8_LDB(B1, 1, 1); PG8_SCHED; PG8_LDA(At, 1, 0); PG8_STAGE(PG8_SA(0, 1), a2 + hstep, voffA);
;             PG8_WAIT_V(8); PG8_WAIT_L(0); PG8_BAR; PG8_MMA(0, 0, At, B0); PG8_MMA(0, 1, At, B1); PG8_BAR; PG8_SCHED;
;             PG8_LDA(At, 1, 1); PG8_STAGE(PG8_SB(1, 0), b3, voffB); PG8_STAGE(PG8_SB(1, 1), b3 + hstep, voffB); PG8_STAGE(PG8_SA(1, 0), a3, voffA);
	s_setprio 1
	s_waitcnt lgkmcnt(0)
	v_mfma_f32_16x16x32_bf16 v[60:63], v[104:107], v[176:179], v[60:63]
	v_mfma_f32_16x16x32_bf16 v[56:59], v[136:139], v[176:179], v[56:59]
	v_mfma_f32_16x16x32_bf16 v[44:47], v[104:107], v[188:191], v[44:47]
	v_mfma_f32_16x16x32_bf16 v[40:43], v[136:139], v[188:191], v[40:43]
	v_mfma_f32_16x16x32_bf16 v[28:31], v[104:107], v[214:217], v[28:31]
	v_mfma_f32_16x16x32_bf16 v[24:27], v[136:139], v[214:217], v[24:27]
	v_mfma_f32_16x16x32_bf16 v[12:15], v[104:107], v[222:225], v[12:15]
	v_mfma_f32_16x16x32_bf16 v[8:11], v[136:139], v[222:225], v[8:11]
	v_mfma_f32_16x16x32_bf16 v[60:63], v[132:135], v[184:187], v[60:63]
	v_mfma_f32_16x16x32_bf16 v[56:59], v[140:143], v[184:187], v[56:59]
	v_mfma_f32_16x16x32_bf16 v[44:47], v[132:135], v[208:211], v[44:47]
	v_mfma_f32_16x16x32_bf16 v[40:43], v[140:143], v[208:211], v[40:43]
	v_mfma_f32_16x16x32_bf16 v[28:31], v[132:135], v[218:221], v[28:31]
	v_mfma_f32_16x16x32_bf16 v[24:27], v[140:143], v[218:221], v[24:27]
	v_mfma_f32_16x16x32_bf16 v[12:15], v[132:135], v[226:229], v[12:15]
	v_mfma_f32_16x16x32_bf16 v[8:11], v[140:143], v[226:229], v[8:11]
	s_setprio 0
	s_setprio 1
	v_mfma_f32_16x16x32_bf16 v[52:55], v[144:147], v[176:179], v[52:55]
	v_mfma_f32_16x16x32_bf16 v[48:51], v[168:171], v[176:179], v[48:51]
	v_mfma_f32_16x16x32_bf16 v[36:39], v[144:147], v[188:191], v[36:39]
	v_mfma_f32_16x16x32_bf16 v[32:35], v[168:171], v[188:191], v[32:35]
	v_mfma_f32_16x16x32_bf16 v[20:23], v[144:147], v[214:217], v[20:23]
	v_mfma_f32_16x16x32_bf16 v[16:19], v[168:171], v[214:217], v[16:19]
	v_mfma_f32_16x16x32_bf16 v[4:7], v[144:147], v[222:225], v[4:7]
	v_mfma_f32_16x16x32_bf16 v[0:3], v[168:171], v[222:225], v[0:3]
	v_mfma_f32_16x16x32_bf16 v[52:55], v[156:159], v[184:187], v[52:55]
	v_mfma_f32_16x16x32_bf16 v[48:51], v[172:175], v[184:187], v[48:51]
	v_mfma_f32_16x16x32_bf16 v[36:39], v[156:159], v[208:211], v[36:39]
	v_mfma_f32_16x16x32_bf16 v[32:35], v[172:175], v[208:211], v[32:35]
	v_mfma_f32_16x16x32_bf16 v[20:23], v[156:159], v[218:221], v[20:23]
	v_mfma_f32_16x16x32_bf16 v[16:19], v[172:175], v[218:221], v[16:19]
	v_mfma_f32_16x16x32_bf16 v[4:7], v[156:159], v[226:229], v[4:7]
	v_mfma_f32_16x16x32_bf16 v[0:3], v[172:175], v[226:229], v[0:3]
	s_setprio 0
	s_barrier
	s_add_i32 s40, 0, 0x18000
	s_add_i32 s41, 0, 0x1c000
	v_add_u32_e32 v140, s40, v167
	v_add_u32_e32 v172, s41, v167
	ds_read_b128 v[104:107], v140
	ds_read_b128 v[132:135], v140 offset:1024
	ds_read_b128 v[136:139], v140 offset:2048
	ds_read_b128 v[140:143], v140 offset:3072
	ds_read_b128 v[144:147], v172
	ds_read_b128 v[156:159], v172 offset:1024
	ds_read_b128 v[168:171], v172 offset:2048
	ds_read_b128 v[172:175], v172 offset:3072
	s_add_u32 s28, s28, s44
	s_addc_u32 s29, s29, 0
	s_mov_b32 m0, s23
	v_lshl_add_u64 v[238:239], s[28:29], 0, v[148:149]
	ds_read_b128 v[176:179], v183 offset:32768
	ds_read_b128 v[184:187], v183 offset:33792
	ds_read_b128 v[188:191], v183 offset:34816
	ds_read_b128 v[208:211], v183 offset:35840
	ds_read_b128 v[214:217], v183 offset:36864
	ds_read_b128 v[218:221], v183 offset:37888
	ds_read_b128 v[222:225], v183 offset:38912
	ds_read_b128 v[226:229], v183 offset:39936
	global_load_lds_dwordx4 v[238:239], off
	v_lshl_add_u64 v[238:239], s[28:29], 0, v[150:151]
	s_mov_b32 m0, s25
	s_nop 0
	global_load_lds_dwordx4 v[238:239], off
	s_waitcnt vmcnt(8)
	s_waitcnt lgkmcnt(0)
	s_barrier
	s_setprio 1
	s_waitcnt lgkmcnt(0)
	v_mfma_f32_16x16x32_bf16 v[128:131], v[104:107], v[176:179], v[128:131]
	v_mfma_f32_16x16x32_bf16 v[124:127], v[136:139], v[176:179], v[124:127]
	v_mfma_f32_16x16x32_bf16 v[112:115], v[104:107], v[188:191], v[112:115]
	v_mfma_f32_16x16x32_bf16 v[108:111], v[136:139], v[188:191], v[108:111]
	v_mfma_f32_16x16x32_bf16 v[92:95], v[104:107], v[214:217], v[92:95]
	v_mfma_f32_16x16x32_bf16 v[88:91], v[136:139], v[214:217], v[88:91]
	v_mfma_f32_16x16x32_bf16 v[76:79], v[104:107], v[222:225], v[76:79]
	v_mfma_f32_16x16x32_bf16 v[72:75], v[136:139], v[222:225], v[72:75]
	v_mfma_f32_16x16x32_bf16 v[128:131], v[132:135], v[184:187], v[128:131]
	v_mfma_f32_16x16x32_bf16 v[124:127], v[140:143], v[184:187], v[124:127]
	v_mfma_f32_16x16x32_bf16 v[112:115], v[132:135], v[208:211], v[112:115]
	v_mfma_f32_16x16x32_bf16 v[108:111], v[140:143], v[208:211], v[108:111]
	v_mfma_f32_16x16x32_bf16 v[92:95], v[132:135], v[218:221], v[92:95]
	v_mfma_f32_16x16x32_bf16 v[88:91], v[140:143], v[218:221], v[88:91]
	v_mfma_f32_16x16x32_bf16 v[76:79], v[132:135], v[226:229], v[76:79]
	v_mfma_f32_16x16x32_bf16 v[72:75], v[140:143], v[226:229], v[72:75]
	s_setprio 0
	s_setprio 1
	v_mfma_f32_16x16x32_bf16 v[120:123], v[144:147], v[176:179], v[120:123]
	v_mfma_f32_16x16x32_bf16 v[116:119], v[168:171], v[176:179], v[116:119]
	v_mfma_f32_16x16x32_bf16 v[100:103], v[144:147], v[188:191], v[100:103]
	v_mfma_f32_16x16x32_bf16 v[96:99], v[168:171], v[188:191], v[96:99]
	v_mfma_f32_16x16x32_bf16 v[84:87], v[144:147], v[214:217], v[84:87]
	v_mfma_f32_16x16x32_bf16 v[80:83], v[168:171], v[214:217], v[80:83]
	v_mfma_f32_16x16x32_bf16 v[68:71], v[144:147], v[222:225], v[68:71]
	v_mfma_f32_16x16x32_bf16 v[64:67], v[168:171], v[222:225], v[64:67]
	v_mfma_f32_16x16x32_bf16 v[120:123], v[156:159], v[184:187], v[120:123]
	v_mfma_f32_16x16x32_bf16 v[116:119], v[172:175], v[184:187], v[116:119]
	v_mfma_f32_16x16x32_bf16 v[100:103], v[156:159], v[208:211], v[100:103]
	v_mfma_f32_16x16x32_bf16 v[96:99], v[172:175], v[208:211], v[96:99]
	v_mfma_f32_16x16x32_bf16 v[84:87], v[156:159], v[218:221], v[84:87]
	v_mfma_f32_16x16x32_bf16 v[80:83], v[172:175], v[218:221], v[80:83]
	v_mfma_f32_16x16x32_bf16 v[68:71], v[156:159], v[226:229], v[68:71]
	v_mfma_f32_16x16x32_bf16 v[64:67], v[172:175], v[226:229], v[64:67]
	s_setprio 0
	s_barrier
; #define PG8_STAGE(bufoff, gbase, voff) do { _Pragma("unroll") for (int _i = 0; _i < 2; ++_i) \
;         __builtin_amdgcn_global_load_lds((const unsigned*)((const char*)(gbase) + (voff)[_i]), (LAS unsigned*)(lds + (bufoff) + ldsw + _i * 8192), 16, 0, 0); } while (0)
; #define PG8_LDA(dst, b, h) do { _Pragma("unroll") for (int m = 0; m < 4; ++m) _Pragma("unroll") for (int k = 0; k < 2; ++k) dst[m][k] = *(const LAS bf16x8*)(lds + PG8_SA(b, h) + aoff + m * 2048 + k * 1024); } while (0)
; #define PG8_MMA(ai, bj, At, Bt) do { __builtin_amdgcn_s_setprio(1); _Pragma("unroll") for (int m = 0; m < 4; ++m) _Pragma("unroll") for (int n = 0; n < 2; ++n) _Pragma("unroll") for (int k = 0; k < 2; ++k) \
;         acc[ai][bj][m][n] = __builtin_amdgcn_mfma_f32_16x16x32_bf16(Bt[n][k], At[m][k], acc[ai][bj][m][n], 0, 0, 0); __builtin_amdgcn_s_setprio(0); } while (0)
; #define PG8_WAIT_V(n) asm volatile("s_waitcnt vmcnt(" #n ")" ::: "memory")
; #define PG8_WAIT_L(n) asm volatile("s_waitcnt lgkmcnt(" #n ")" ::: "memory")
; #define PG8_BAR __builtin_amdgcn_s_barrier()
; #define PG8_SCHED __builtin_amdgcn_sched_barrier(0)
; template <class Epi, bool ALIGN_EPI, bool SP2>
; __device__ __forceinline__ void gemm_phase(LAS unsigned char* lds, const Gemm g, const StaticOrder& S, const Epi& E, const int tid) {
;     ...
;         for (int t = 0; t < nt; t += 2) {
;             const bool last = (t == nt - 2);
;             const char* a1 = cA + (size_t)(t + 1) * kstep;
;             const char* a2 = last ? nA : cA + (size_t)(t + 2) * kstep; const char* b2 = last ? nB : cB + (size_t)(t + 2) * kstep;
;             const char* a3 = a2 + kstep; const char* b3 = b2 + kstep;
;     ...
;             PG8_LDA(At, 1, 1); PG8_STAGE(PG8_SB(1, 0), b3, voffB); PG8_STAGE(PG8_SB(1, 1), b3 + hstep, voffB); PG8_STAGE(PG8_SA(1, 0), a3, voffA);
;             PG8_WAIT_V(8); PG8_WAIT_L(0); PG8_BAR; PG8_MMA(1, 0, At, B0); PG8_MMA(1, 1, At, B1); PG8_BAR; PG8_SCHED;
	s_add_i32 s28, s40, s14
	v_lshl_add_u64 v[180:181], v[180:181], 0, s[8:9]
	s_mov_b32 m0, s28
	ds_read_b128 v[176:179], v183 offset:49152
	ds_read_b128 v[184:187], v183 offset:50176
	ds_read_b128 v[188:191], v183 offset:51200
	ds_read_b128 v[208:211], v183 offset:52224
	ds_read_b128 v[214:217], v183 offset:53248
	ds_read_b128 v[218:221], v183 offset:54272
	ds_read_b128 v[222:225], v183 offset:55296
	ds_read_b128 v[226:229], v183 offset:56320
	global_load_lds_dwordx4 v[180:181], off
	v_lshl_add_u64 v[180:181], v[192:193], 0, s[8:9]
	s_add_i32 m0, s28, 0x2000
	s_add_i32 s28, s41, s14
	global_load_lds_dwordx4 v[180:181], off
	v_lshl_add_u64 v[180:181], v[230:231], 0, s[8:9]
	s_mov_b32 m0, s28
	s_nop 0
	global_load_lds_dwordx4 v[180:181], off
	v_lshl_add_u64 v[180:181], v[232:233], 0, s[8:9]
	s_add_i32 m0, s28, 0x2000
	s_nop 0
	global_load_lds_dwordx4 v[180:181], off
	v_lshl_add_u64 v[180:181], v[234:235], 0, s[8:9]
	s_mov_b32 m0, s54
	s_nop 0
	global_load_lds_dwordx4 v[180:181], off
	v_lshl_add_u64 v[180:181], v[236:237], 0, s[8:9]
	s_mov_b32 m0, s55
	s_nop 0
	global_load_lds_dwordx4 v[180:181], off
	s_waitcnt vmcnt(8)
	s_waitcnt lgkmcnt(0)
	s_barrier
	s_setprio 1
	s_waitcnt lgkmcnt(0)
	v_mfma_f32_16x16x32_bf16 v[60:63], v[104:107], v[176:179], v[60:63]
	v_mfma_f32_16x16x32_bf16 v[56:59], v[136:139], v[176:179], v[56:59]
	v_mfma_f32_16x16x32_bf16 v[44:47], v[104:107], v[188:191], v[44:47]
	v_mfma_f32_16x16x32_bf16 v[40:43], v[136:139], v[188:191], v[40:43]
	v_mfma_f32_16x16x32_bf16 v[28:31], v[104:107], v[214:217], v[28:31]
	v_mfma_f32_16x16x32_bf16 v[24:27], v[136:139], v[214:217], v[24:27]
	v_mfma_f32_16x16x32_bf16 v[12:15], v[104:107], v[222:225], v[12:15]
	v_mfma_f32_16x16x32_bf16 v[8:11], v[136:139], v[222:225], v[8:11]
	v_mfma_f32_16x16x32_bf16 v[60:63], v[132:135], v[184:187], v[60:63]
	v_mfma_f32_16x16x32_bf16 v[56:59], v[140:143], v[184:187], v[56:59]
	v_mfma_f32_16x16x32_bf16 v[44:47], v[132:135], v[208:211], v[44:47]
	v_mfma_f32_16x16x32_bf16 v[40:43], v[140:143], v[208:211], v[40:43]
	v_mfma_f32_16x16x32_bf16 v[28:31], v[132:135], v[218:221], v[28:31]
	v_mfma_f32_16x16x32_bf16 v[24:27], v[140:143], v[218:221], v[24:27]
	v_mfma_f32_16x16x32_bf16 v[12:15], v[132:135], v[226:229], v[12:15]
	v_mfma_f32_16x16x32_bf16 v[8:11], v[140:143], v[226:229], v[8:11]
	s_setprio 0
	s_setprio 1
	v_mfma_f32_16x16x32_bf16 v[52:55], v[144:147], v[176:179], v[52:55]
	s_add_u32 s0, s0, 0x100
	s_addc_u32 s1, s1, 0
	v_mfma_f32_16x16x32_bf16 v[48:51], v[168:171], v[176:179], v[48:51]
	s_add_u32 s34, s34, 0x100
	s_addc_u32 s35, s35, 0
	v_mfma_f32_16x16x32_bf16 v[36:39], v[144:147], v[188:191], v[36:39]
	s_mov_b32 s28, s36
	s_add_i32 s36, s28, 2
	v_mfma_f32_16x16x32_bf16 v[32:35], v[168:171], v[188:191], v[32:35]
	s_add_u32 s40, s0, 0x80
	s_addc_u32 s29, s1, 0
	v_mfma_f32_16x16x32_bf16 v[20:23], v[144:147], v[214:217], v[20:23]
	s_add_i32 s42, 0, 0x10000
	s_cmp_eq_u32 s49, s28
	v_mfma_f32_16x16x32_bf16 v[16:19], v[168:171], v[214:217], v[16:19]
	s_cselect_b32 s29, s19, s29
	s_cselect_b32 s28, s18, s40
	v_mfma_f32_16x16x32_bf16 v[4:7], v[144:147], v[222:225], v[4:7]
	s_cselect_b32 s41, s97, s35
	s_cselect_b32 s40, s96, s34
	v_mfma_f32_16x16x32_bf16 v[0:3], v[168:171], v[222:225], v[0:3]
	s_add_i32 s43, 0, 0x14000
	v_mfma_f32_16x16x32_bf16 v[52:55], v[156:159], v[184:187], v[52:55]
	s_add_i32 vcc_lo, s46, 2
	s_cmp_ge_u32 s36, vcc_lo
	v_mfma_f32_16x16x32_bf16 v[48:51], v[172:175], v[184:187], v[48:51]
	v_mfma_f32_16x16x32_bf16 v[36:39], v[156:159], v[208:211], v[36:39]
	v_mfma_f32_16x16x32_bf16 v[32:35], v[172:175], v[208:211], v[32:35]
	v_mfma_f32_16x16x32_bf16 v[20:23], v[156:159], v[218:221], v[20:23]
	v_mfma_f32_16x16x32_bf16 v[16:19], v[172:175], v[218:221], v[16:19]
	v_mfma_f32_16x16x32_bf16 v[4:7], v[156:159], v[226:229], v[4:7]
	v_mfma_f32_16x16x32_bf16 v[0:3], v[172:175], v[226:229], v[0:3]
	s_setprio 0
	s_barrier
	s_cbranch_scc0 .Lk398_head
	s_and_b64 vcc, exec, s[50:51]
	s_cbranch_vccz .LBB0_401
	s_barrier

; #define PG8_STAGE(bufoff, gbase, voff) do { _Pragma("unroll") for (int _i = 0; _i < 2; ++_i) \
;         __builtin_amdgcn_global_load_lds((const unsigned*)((const char*)(gbase) + (voff)[_i]), (LAS unsigned*)(lds + (bufoff) + ldsw + _i * 8192), 16, 0, 0); } while (0)
; #define PG8_LDA(dst, b, h) do { _Pragma("unroll") for (int m = 0; m < 4; ++m) _Pragma("unroll") for (int k = 0; k < 2; ++k) dst[m][k] = *(const LAS bf16x8*)(lds + PG8_SA(b, h) + aoff + m * 2048 + k * 1024); } while (0)
; #define PG8_LDB(dst, b, h) do { _Pragma("unroll") for (int n = 0; n < 2; ++n) _Pragma("unroll") for (int k = 0; k < 2; ++k) dst[n][k] = *(const LAS bf16x8*)(lds + PG8_SB(b, h) + boff + n * 2048 + k * 1024); } while (0)
; #define PG8_MMA(ai, bj, At, Bt) do { __builtin_amdgcn_s_setprio(1); _Pragma("unroll") for (int m = 0; m < 4; ++m) _Pragma("unroll") for (int n = 0; n < 2; ++n) _Pragma("unroll") for (int k = 0; k < 2; ++k) \
;         acc[ai][bj][m][n] = __builtin_amdgcn_mfma_f32_16x16x32_bf16(Bt[n][k], At[m][k], acc[ai][bj][m][n], 0, 0, 0); __builtin_amdgcn_s_setprio(0); } while (0)
; #define PG8_WAIT_V(n) asm volatile("s_waitcnt vmcnt(" #n ")" ::: "memory")
; #define PG8_WAIT_L(n) asm volatile("s_waitcnt lgkmcnt(" #n ")" ::: "memory")
; #define PG8_BAR __builtin_amdgcn_s_barrier()
; #define PG8_SCHED __builtin_amdgcn_sched_barrier(0)
; template <class Epi, bool ALIGN_EPI, bool SP2>
; __device__ __forceinline__ void gemm_phase(LAS unsigned char* lds, const Gemm g, const StaticOrder& S, const Epi& E, const int tid) {
;     ...
;             PG8_LDB(B0, 0, 0); PG8_LDB(B1, 0, 1); PG8_SCHED; PG8_LDA(At, 0, 0); PG8_STAGE(PG8_SA(1, 1), a1 + hstep, voffA);
;             PG8_WAIT_V(8); PG8_WAIT_L(0); PG8_BAR; PG8_MMA(0, 0, At, B0); PG8_MMA(0, 1, At, B1); PG8_BAR; PG8_SCHED;
;             PG8_LDA(At, 0, 1); PG8_STAGE(PG8_SB(0, 0), b2, voffB); PG8_STAGE(PG8_SB(0, 1), b2 + hstep, voffB); PG8_STAGE(PG8_SA(0, 0), a2, voffA);
;             PG8_WAIT_V(8); PG8_WAIT_L(0); PG8_BAR; PG8_MMA(1, 0, At, B0); PG8_MMA(1, 1, At, B1); PG8_BAR; PG8_SCHED;
.Lk473_head:
	v_add_u32_e32 v140, s76, v167
	v_add_u32_e32 v171, s51, v167
	ds_read_b128 v[120:123], v140
	ds_read_b128 v[124:127], v140 offset:1024
	ds_read_b128 v[136:139], v140 offset:2048
	ds_read_b128 v[140:143], v140 offset:3072
	ds_read_b128 v[144:147], v171
	ds_read_b128 v[148:151], v171 offset:1024
	ds_read_b128 v[172:175], v171 offset:2048
	ds_read_b128 v[176:179], v171 offset:3072
	v_lshl_add_u64 v[230:231], s[0:1], 0, v[158:159]
	s_add_i32 m0, s13, 0xc000
	ds_read_b128 v[180:183], v185
	ds_read_b128 v[186:189], v185 offset:1024
	ds_read_b128 v[190:193], v185 offset:2048
	ds_read_b128 v[208:211], v185 offset:3072
	ds_read_b128 v[214:217], v185 offset:4096
	ds_read_b128 v[218:221], v185 offset:5120
	ds_read_b128 v[222:225], v185 offset:6144
	ds_read_b128 v[226:229], v185 offset:7168
	global_load_lds_dwordx4 v[230:231], off
	v_lshl_add_u64 v[230:231], s[0:1], 0, v[168:169]
	s_add_i32 m0, s13, 0xe000
	s_nop 0
	global_load_lds_dwordx4 v[230:231], off
	s_waitcnt vmcnt(8)
	s_waitcnt lgkmcnt(0)
	s_barrier
	s_setprio 1
	s_waitcnt lgkmcnt(0)
	v_mfma_f32_16x16x32_bf16 v[132:135], v[120:123], v[180:183], v[132:135]
	v_mfma_f32_16x16x32_bf16 v[128:131], v[136:139], v[180:183], v[128:131]
	v_mfma_f32_16x16x32_bf16 v[108:111], v[120:123], v[190:193], v[108:111]
	v_mfma_f32_16x16x32_bf16 v[104:107], v[136:139], v[190:193], v[104:107]
	v_mfma_f32_16x16x32_bf16 v[92:95], v[120:123], v[214:217], v[92:95]
	v_mfma_f32_16x16x32_bf16 v[88:91], v[136:139], v[214:217], v[88:91]
	v_mfma_f32_16x16x32_bf16 v[76:79], v[120:123], v[222:225], v[76:79]
	v_mfma_f32_16x16x32_bf16 v[72:75], v[136:139], v[222:225], v[72:75]
	v_mfma_f32_16x16x32_bf16 v[132:135], v[124:127], v[186:189], v[132:135]
	v_mfma_f32_16x16x32_bf16 v[128:131], v[140:143], v[186:189], v[128:131]
	v_mfma_f32_16x16x32_bf16 v[108:111], v[124:127], v[208:211], v[108:111]
	v_mfma_f32_16x16x32_bf16 v[104:107], v[140:143], v[208:211], v[104:107]
	v_mfma_f32_16x16x32_bf16 v[92:95], v[124:127], v[218:221], v[92:95]
	v_mfma_f32_16x16x32_bf16 v[88:91], v[140:143], v[218:221], v[88:91]
	v_mfma_f32_16x16x32_bf16 v[76:79], v[124:127], v[226:229], v[76:79]
	v_mfma_f32_16x16x32_bf16 v[72:75], v[140:143], v[226:229], v[72:75]
	s_setprio 0
	s_setprio 1
	v_mfma_f32_16x16x32_bf16 v[116:119], v[144:147], v[180:183], v[116:119]
	v_mfma_f32_16x16x32_bf16 v[112:115], v[172:175], v[180:183], v[112:115]
	v_mfma_f32_16x16x32_bf16 v[100:103], v[144:147], v[190:193], v[100:103]
	v_mfma_f32_16x16x32_bf16 v[96:99], v[172:175], v[190:193], v[96:99]
	v_mfma_f32_16x16x32_bf16 v[84:87], v[144:147], v[214:217], v[84:87]
	v_mfma_f32_16x16x32_bf16 v[80:83], v[172:175], v[214:217], v[80:83]
	v_mfma_f32_16x16x32_bf16 v[68:71], v[144:147], v[222:225], v[68:71]
	v_mfma_f32_16x16x32_bf16 v[64:67], v[172:175], v[222:225], v[64:67]
	v_mfma_f32_16x16x32_bf16 v[116:119], v[148:151], v[186:189], v[116:119]
	v_mfma_f32_16x16x32_bf16 v[112:115], v[176:179], v[186:189], v[112:115]
	v_mfma_f32_16x16x32_bf16 v[100:103], v[148:151], v[208:211], v[100:103]
	v_mfma_f32_16x16x32_bf16 v[96:99], v[176:179], v[208:211], v[96:99]
	v_mfma_f32_16x16x32_bf16 v[84:87], v[148:151], v[218:221], v[84:87]
	v_mfma_f32_16x16x32_bf16 v[80:83], v[176:179], v[218:221], v[80:83]
	v_mfma_f32_16x16x32_bf16 v[68:71], v[148:151], v[226:229], v[68:71]
	v_mfma_f32_16x16x32_bf16 v[64:67], v[176:179], v[226:229], v[64:67]
	s_setprio 0
	s_barrier
	s_add_i32 s76, s76, s12
	v_lshl_add_u64 v[230:231], s[74:75], 0, v[152:153]
	s_mov_b32 m0, s76
	ds_read_b128 v[180:183], v185 offset:16384
	ds_read_b128 v[186:189], v185 offset:17408
	ds_read_b128 v[190:193], v185 offset:18432
	ds_read_b128 v[208:211], v185 offset:19456
	ds_read_b128 v[214:217], v185 offset:20480
	ds_read_b128 v[218:221], v185 offset:21504
	ds_read_b128 v[222:225], v185 offset:22528
	ds_read_b128 v[226:229], v185 offset:23552
	global_load_lds_dwordx4 v[230:231], off
	s_add_i32 m0, s76, 0x2000
	v_lshl_add_u64 v[232:233], s[74:75], 0, v[154:155]
	s_add_u32 s74, s74, s36
	s_addc_u32 s75, s75, 0
	s_add_i32 s51, s51, s12
	global_load_lds_dwordx4 v[232:233], off
	v_lshl_add_u64 v[234:235], s[74:75], 0, v[152:153]
	s_mov_b32 m0, s51
	v_lshl_add_u64 v[236:237], s[74:75], 0, v[154:155]
	global_load_lds_dwordx4 v[234:235], off
	s_add_i32 m0, s51, 0x2000
	v_lshl_add_u64 v[238:239], s[34:35], 0, v[152:153]
	global_load_lds_dwordx4 v[236:237], off
	s_mov_b32 m0, s13
	v_lshl_add_u64 v[240:241], s[34:35], 0, v[154:155]
	global_load_lds_dwordx4 v[238:239], off
	s_mov_b32 m0, s14
	s_nop 0
	global_load_lds_dwordx4 v[240:241], off
	s_waitcnt vmcnt(8)
	s_waitcnt lgkmcnt(0)
	s_barrier
; #define PG8_STAGE(bufoff, gbase, voff) do { _Pragma("unroll") for (int _i = 0; _i < 2; ++_i) \
;         __builtin_amdgcn_global_load_lds((const unsigned*)((const char*)(gbase) + (voff)[_i]), (LAS unsigned*)(lds + (bufoff) + ldsw + _i * 8192), 16, 0, 0); } while (0)
; #define PG8_LDA(dst, b, h) do { _Pragma("unroll") for (int m = 0; m < 4; ++m) _Pragma("unroll") for (int k = 0; k < 2; ++k) dst[m][k] = *(const LAS bf16x8*)(lds + PG8_SA(b, h) + aoff + m * 2048 + k * 1024); } while (0)
; #define PG8_LDB(dst, b, h) do { _Pragma("unroll") for (int n = 0; n < 2; ++n) _Pragma("unroll") for (int k = 0; k < 2; ++k) dst[n][k] = *(const LAS bf16x8*)(lds + PG8_SB(b, h) + boff + n * 2048 + k * 1024); } while (0)
; #define PG8_MMA(ai, bj, At, Bt) do { __builtin_amdgcn_s_setprio(1); _Pragma("unroll") for (int m = 0; m < 4; ++m) _Pragma("unroll") for (int n = 0; n < 2; ++n) _Pragma("unroll") for (int k = 0; k < 2; ++k) \
;         acc[ai][bj][m][n] = __builtin_amdgcn_mfma_f32_16x16x32_bf16(Bt[n][k], At[m][k], acc[ai][bj][m][n], 0, 0, 0); __builtin_amdgcn_s_setprio(0); } while (0)
; #define PG8_WAIT_V(n) asm volatile("s_waitcnt vmcnt(" #n ")" ::: "memory")
; #define PG8_WAIT_L(n) asm volatile("s_waitcnt lgkmcnt(" #n ")" ::: "memory")
; #define PG8_BAR __builtin_amdgcn_s_barrier()
; #define PG8_SCHED __builtin_amdgcn_sched_barrier(0)
; template <class Epi, bool ALIGN_EPI, bool SP2>
; __device__ __forceinline__ void gemm_phase(LAS unsigned char* lds, const Gemm g, const StaticOrder& S, const Epi& E, const int tid) {
;     ...
;             PG8_LDA(At, 0, 1); PG8_STAGE(PG8_SB(0, 0), b2, voffB); PG8_STAGE(PG8_SB(0, 1), b2 + hstep, voffB); PG8_STAGE(PG8_SA(0, 0), a2, voffA);
;             PG8_WAIT_V(8); PG8_WAIT_L(0); PG8_BAR; PG8_MMA(1, 0, At, B0); PG8_MMA(1, 1, At, B1); PG8_BAR; PG8_SCHED;
;             PG8_LDB(B0, 1, 0); PG8_LDB(B1, 1, 1); PG8_SCHED; PG8_LDA(At, 1, 0); PG8_STAGE(PG8_SA(0, 1), a2 + hstep, voffA);
;             PG8_WAIT_V(8); PG8_WAIT_L(0); PG8_BAR; PG8_MMA(0, 0, At, B0); PG8_MMA(0, 1, At, B1); PG8_BAR; PG8_SCHED;
;             PG8_LDA(At, 1, 1); PG8_STAGE(PG8_SB(1, 0), b3, voffB); PG8_STAGE(PG8_SB(1, 1), b3 + hstep, voffB); PG8_STAGE(PG8_SA(1, 0), a3, voffA);
	s_setprio 1
	s_waitcnt lgkmcnt(0)
	v_mfma_f32_16x16x32_bf16 v[60:63], v[120:123], v[180:183], v[60:63]
	v_mfma_f32_16x16x32_bf16 v[56:59], v[136:139], v[180:183], v[56:59]
	v_mfma_f32_16x16x32_bf16 v[44:47], v[120:123], v[190:193], v[44:47]
	v_mfma_f32_16x16x32_bf16 v[40:43], v[136:139], v[190:193], v[40:43]
	v_mfma_f32_16x16x32_bf16 v[28:31], v[120:123], v[214:217], v[28:31]
	v_mfma_f32_16x16x32_bf16 v[24:27], v[136:139], v[214:217], v[24:27]
	v_mfma_f32_16x16x32_bf16 v[12:15], v[120:123], v[222:225], v[12:15]
	v_mfma_f32_16x16x32_bf16 v[8:11], v[136:139], v[222:225], v[8:11]
	v_mfma_f32_16x16x32_bf16 v[60:63], v[124:127], v[186:189], v[60:63]
	v_mfma_f32_16x16x32_bf16 v[56:59], v[140:143], v[186:189], v[56:59]
	v_mfma_f32_16x16x32_bf16 v[44:47], v[124:127], v[208:211], v[44:47]
	v_mfma_f32_16x16x32_bf16 v[40:43], v[140:143], v[208:211], v[40:43]
	v_mfma_f32_16x16x32_bf16 v[28:31], v[124:127], v[218:221], v[28:31]
	v_mfma_f32_16x16x32_bf16 v[24:27], v[140:143], v[218:221], v[24:27]
	v_mfma_f32_16x16x32_bf16 v[12:15], v[124:127], v[226:229], v[12:15]
	v_mfma_f32_16x16x32_bf16 v[8:11], v[140:143], v[226:229], v[8:11]
	s_setprio 0
	s_setprio 1
	v_mfma_f32_16x16x32_bf16 v[52:55], v[144:147], v[180:183], v[52:55]
	v_mfma_f32_16x16x32_bf16 v[48:51], v[172:175], v[180:183], v[48:51]
	v_mfma_f32_16x16x32_bf16 v[36:39], v[144:147], v[190:193], v[36:39]
	v_mfma_f32_16x16x32_bf16 v[32:35], v[172:175], v[190:193], v[32:35]
	v_mfma_f32_16x16x32_bf16 v[20:23], v[144:147], v[214:217], v[20:23]
	v_mfma_f32_16x16x32_bf16 v[16:19], v[172:175], v[214:217], v[16:19]
	v_mfma_f32_16x16x32_bf16 v[4:7], v[144:147], v[222:225], v[4:7]
	v_mfma_f32_16x16x32_bf16 v[0:3], v[172:175], v[222:225], v[0:3]
	v_mfma_f32_16x16x32_bf16 v[52:55], v[148:151], v[186:189], v[52:55]
	v_mfma_f32_16x16x32_bf16 v[48:51], v[176:179], v[186:189], v[48:51]
	v_mfma_f32_16x16x32_bf16 v[36:39], v[148:151], v[208:211], v[36:39]
	v_mfma_f32_16x16x32_bf16 v[32:35], v[176:179], v[208:211], v[32:35]
	v_mfma_f32_16x16x32_bf16 v[20:23], v[148:151], v[218:221], v[20:23]
	v_mfma_f32_16x16x32_bf16 v[16:19], v[176:179], v[218:221], v[16:19]
	v_mfma_f32_16x16x32_bf16 v[4:7], v[148:151], v[226:229], v[4:7]
	v_mfma_f32_16x16x32_bf16 v[0:3], v[176:179], v[226:229], v[0:3]
	s_setprio 0
	s_barrier
	s_add_i32 s51, 0, 0x18000
	s_add_i32 s74, 0, 0x1c000
	v_add_u32_e32 v140, s51, v167
	v_add_u32_e32 v171, s74, v167
	ds_read_b128 v[120:123], v140
	ds_read_b128 v[124:127], v140 offset:1024
	ds_read_b128 v[136:139], v140 offset:2048
	ds_read_b128 v[140:143], v140 offset:3072
	ds_read_b128 v[144:147], v171
	ds_read_b128 v[148:151], v171 offset:1024
	ds_read_b128 v[172:175], v171 offset:2048
	ds_read_b128 v[176:179], v171 offset:3072
	s_add_u32 s34, s34, s36
	s_addc_u32 s35, s35, 0
	s_mov_b32 m0, s15
	v_lshl_add_u64 v[242:243], s[34:35], 0, v[152:153]
	ds_read_b128 v[180:183], v185 offset:32768
	ds_read_b128 v[186:189], v185 offset:33792
	ds_read_b128 v[190:193], v185 offset:34816
	ds_read_b128 v[208:211], v185 offset:35840
	ds_read_b128 v[214:217], v185 offset:36864
	ds_read_b128 v[218:221], v185 offset:37888
	ds_read_b128 v[222:225], v185 offset:38912
	ds_read_b128 v[226:229], v185 offset:39936
	global_load_lds_dwordx4 v[242:243], off
	v_lshl_add_u64 v[242:243], s[34:35], 0, v[154:155]
	s_mov_b32 m0, s22
	s_nop 0
	global_load_lds_dwordx4 v[242:243], off
	s_waitcnt vmcnt(8)
	s_waitcnt lgkmcnt(0)
	s_barrier
	s_setprio 1
	s_waitcnt lgkmcnt(0)
	v_mfma_f32_16x16x32_bf16 v[132:135], v[120:123], v[180:183], v[132:135]
	v_mfma_f32_16x16x32_bf16 v[128:131], v[136:139], v[180:183], v[128:131]
	v_mfma_f32_16x16x32_bf16 v[108:111], v[120:123], v[190:193], v[108:111]
	v_mfma_f32_16x16x32_bf16 v[104:107], v[136:139], v[190:193], v[104:107]
	v_mfma_f32_16x16x32_bf16 v[92:95], v[120:123], v[214:217], v[92:95]
	v_mfma_f32_16x16x32_bf16 v[88:91], v[136:139], v[214:217], v[88:91]
	v_mfma_f32_16x16x32_bf16 v[76:79], v[120:123], v[222:225], v[76:79]
	v_mfma_f32_16x16x32_bf16 v[72:75], v[136:139], v[222:225], v[72:75]
	v_mfma_f32_16x16x32_bf16 v[132:135], v[124:127], v[186:189], v[132:135]
	v_mfma_f32_16x16x32_bf16 v[128:131], v[140:143], v[186:189], v[128:131]
	v_mfma_f32_16x16x32_bf16 v[108:111], v[124:127], v[208:211], v[108:111]
	v_mfma_f32_16x16x32_bf16 v[104:107], v[140:143], v[208:211], v[104:107]
	v_mfma_f32_16x16x32_bf16 v[92:95], v[124:127], v[218:221], v[92:95]
	v_mfma_f32_16x16x32_bf16 v[88:91], v[140:143], v[218:221], v[88:91]
	v_mfma_f32_16x16x32_bf16 v[76:79], v[124:127], v[226:229], v[76:79]
	v_mfma_f32_16x16x32_bf16 v[72:75], v[140:143], v[226:229], v[72:75]
	s_setprio 0
	s_setprio 1
	v_mfma_f32_16x16x32_bf16 v[116:119], v[144:147], v[180:183], v[116:119]
	v_mfma_f32_16x16x32_bf16 v[112:115], v[172:175], v[180:183], v[112:115]
	v_mfma_f32_16x16x32_bf16 v[100:103], v[144:147], v[190:193], v[100:103]
	v_mfma_f32_16x16x32_bf16 v[96:99], v[172:175], v[190:193], v[96:99]
	v_mfma_f32_16x16x32_bf16 v[84:87], v[144:147], v[214:217], v[84:87]
	v_mfma_f32_16x16x32_bf16 v[80:83], v[172:175], v[214:217], v[80:83]
	v_mfma_f32_16x16x32_bf16 v[68:71], v[144:147], v[222:225], v[68:71]
	v_mfma_f32_16x16x32_bf16 v[64:67], v[172:175], v[222:225], v[64:67]
	v_mfma_f32_16x16x32_bf16 v[116:119], v[148:151], v[186:189], v[116:119]
	v_mfma_f32_16x16x32_bf16 v[112:115], v[176:179], v[186:189], v[112:115]
	v_mfma_f32_16x16x32_bf16 v[100:103], v[148:151], v[208:211], v[100:103]
	v_mfma_f32_16x16x32_bf16 v[96:99], v[176:179], v[208:211], v[96:99]
	v_mfma_f32_16x16x32_bf16 v[84:87], v[148:151], v[218:221], v[84:87]
	v_mfma_f32_16x16x32_bf16 v[80:83], v[176:179], v[218:221], v[80:83]
	v_mfma_f32_16x16x32_bf16 v[68:71], v[148:151], v[226:229], v[68:71]
	v_mfma_f32_16x16x32_bf16 v[64:67], v[176:179], v[226:229], v[64:67]
	s_setprio 0
	s_barrier
; #define PG8_STAGE(bufoff, gbase, voff) do { _Pragma("unroll") for (int _i = 0; _i < 2; ++_i) \
;         __builtin_amdgcn_global_load_lds((const unsigned*)((const char*)(gbase) + (voff)[_i]), (LAS unsigned*)(lds + (bufoff) + ldsw + _i * 8192), 16, 0, 0); } while (0)
; #define PG8_LDA(dst, b, h) do { _Pragma("unroll") for (int m = 0; m < 4; ++m) _Pragma("unroll") for (int k = 0; k < 2; ++k) dst[m][k] = *(const LAS bf16x8*)(lds + PG8_SA(b, h) + aoff + m * 2048 + k * 1024); } while (0)
; #define PG8_MMA(ai, bj, At, Bt) do { __builtin_amdgcn_s_setprio(1); _Pragma("unroll") for (int m = 0; m < 4; ++m) _Pragma("unroll") for (int n = 0; n < 2; ++n) _Pragma("unroll") for (int k = 0; k < 2; ++k) \
;         acc[ai][bj][m][n] = __builtin_amdgcn_mfma_f32_16x16x32_bf16(Bt[n][k], At[m][k], acc[ai][bj][m][n], 0, 0, 0); __builtin_amdgcn_s_setprio(0); } while (0)
; #define PG8_WAIT_V(n) asm volatile("s_waitcnt vmcnt(" #n ")" ::: "memory")
; #define PG8_WAIT_L(n) asm volatile("s_waitcnt lgkmcnt(" #n ")" ::: "memory")
; #define PG8_BAR __builtin_amdgcn_s_barrier()
; #define PG8_SCHED __builtin_amdgcn_sched_barrier(0)
; template <class Epi, bool ALIGN_EPI, bool SP2>
; __device__ __forceinline__ void gemm_phase(LAS unsigned char* lds, const Gemm g, const StaticOrder& S, const Epi& E, const int tid) {
;     ...
;         for (int t = 0; t < nt; t += 2) {
;             const bool last = (t == nt - 2);
;             const char* a1 = cA + (size_t)(t + 1) * kstep;
;             const char* a2 = last ? nA : cA + (size_t)(t + 2) * kstep; const char* b2 = last ? nB : cB + (size_t)(t + 2) * kstep;
;             const char* a3 = a2 + kstep; const char* b3 = b2 + kstep;
;     ...
;             PG8_LDA(At, 1, 1); PG8_STAGE(PG8_SB(1, 0), b3, voffB); PG8_STAGE(PG8_SB(1, 1), b3 + hstep, voffB); PG8_STAGE(PG8_SA(1, 0), a3, voffA);
;             PG8_WAIT_V(8); PG8_WAIT_L(0); PG8_BAR; PG8_MMA(1, 0, At, B0); PG8_MMA(1, 1, At, B1); PG8_BAR; PG8_SCHED;
	s_add_i32 s34, s51, s12
	v_lshl_add_u64 v[230:231], v[230:231], 0, s[8:9]
	s_mov_b32 m0, s34
	ds_read_b128 v[180:183], v185 offset:49152
	ds_read_b128 v[186:189], v185 offset:50176
	ds_read_b128 v[190:193], v185 offset:51200
	ds_read_b128 v[208:211], v185 offset:52224
	ds_read_b128 v[214:217], v185 offset:53248
	ds_read_b128 v[218:221], v185 offset:54272
	ds_read_b128 v[222:225], v185 offset:55296
	ds_read_b128 v[226:229], v185 offset:56320
	global_load_lds_dwordx4 v[230:231], off
	v_lshl_add_u64 v[230:231], v[232:233], 0, s[8:9]
	s_add_i32 m0, s34, 0x2000
	s_add_i32 s34, s74, s12
	global_load_lds_dwordx4 v[230:231], off
	v_lshl_add_u64 v[230:231], v[234:235], 0, s[8:9]
	s_mov_b32 m0, s34
	s_nop 0
	global_load_lds_dwordx4 v[230:231], off
	v_lshl_add_u64 v[230:231], v[236:237], 0, s[8:9]
	s_add_i32 m0, s34, 0x2000
	s_nop 0
	global_load_lds_dwordx4 v[230:231], off
	v_lshl_add_u64 v[230:231], v[238:239], 0, s[8:9]
	s_mov_b32 m0, s4
	s_nop 0
	global_load_lds_dwordx4 v[230:231], off
	v_lshl_add_u64 v[230:231], v[240:241], 0, s[8:9]
	s_mov_b32 m0, s23
	s_nop 0
	global_load_lds_dwordx4 v[230:231], off
	s_waitcnt vmcnt(8)
	s_waitcnt lgkmcnt(0)
	s_barrier
	s_setprio 1
	s_waitcnt lgkmcnt(0)
	v_mfma_f32_16x16x32_bf16 v[60:63], v[120:123], v[180:183], v[60:63]
	v_mfma_f32_16x16x32_bf16 v[56:59], v[136:139], v[180:183], v[56:59]
	v_mfma_f32_16x16x32_bf16 v[44:47], v[120:123], v[190:193], v[44:47]
	v_mfma_f32_16x16x32_bf16 v[40:43], v[136:139], v[190:193], v[40:43]
	v_mfma_f32_16x16x32_bf16 v[28:31], v[120:123], v[214:217], v[28:31]
	v_mfma_f32_16x16x32_bf16 v[24:27], v[136:139], v[214:217], v[24:27]
	v_mfma_f32_16x16x32_bf16 v[12:15], v[120:123], v[222:225], v[12:15]
	v_mfma_f32_16x16x32_bf16 v[8:11], v[136:139], v[222:225], v[8:11]
	v_mfma_f32_16x16x32_bf16 v[60:63], v[124:127], v[186:189], v[60:63]
	v_mfma_f32_16x16x32_bf16 v[56:59], v[140:143], v[186:189], v[56:59]
	v_mfma_f32_16x16x32_bf16 v[44:47], v[124:127], v[208:211], v[44:47]
	v_mfma_f32_16x16x32_bf16 v[40:43], v[140:143], v[208:211], v[40:43]
	v_mfma_f32_16x16x32_bf16 v[28:31], v[124:127], v[218:221], v[28:31]
	v_mfma_f32_16x16x32_bf16 v[24:27], v[140:143], v[218:221], v[24:27]
	v_mfma_f32_16x16x32_bf16 v[12:15], v[124:127], v[226:229], v[12:15]
	v_mfma_f32_16x16x32_bf16 v[8:11], v[140:143], v[226:229], v[8:11]
	s_setprio 0
	s_setprio 1
	v_mfma_f32_16x16x32_bf16 v[52:55], v[144:147], v[180:183], v[52:55]
	s_add_u32 s0, s0, 0x100
	s_addc_u32 s1, s1, 0
	v_mfma_f32_16x16x32_bf16 v[48:51], v[172:175], v[180:183], v[48:51]
	s_add_u32 s44, s44, 0x100
	s_addc_u32 s45, s45, 0
	v_mfma_f32_16x16x32_bf16 v[36:39], v[144:147], v[190:193], v[36:39]
	s_mov_b32 s34, s50
	s_add_i32 s50, s34, 2
	v_mfma_f32_16x16x32_bf16 v[32:35], v[172:175], v[190:193], v[32:35]
	s_add_u32 s51, s0, 0x80
	s_addc_u32 s35, s1, 0
	v_mfma_f32_16x16x32_bf16 v[20:23], v[144:147], v[214:217], v[20:23]
	s_add_i32 s76, 0, 0x10000
	s_cmp_eq_u32 s55, s34
	v_mfma_f32_16x16x32_bf16 v[16:19], v[172:175], v[214:217], v[16:19]
	s_cselect_b32 s35, s49, s35
	s_cselect_b32 s34, s48, s51
	v_mfma_f32_16x16x32_bf16 v[4:7], v[144:147], v[222:225], v[4:7]
	s_cselect_b32 s75, s29, s45
	s_cselect_b32 s74, s28, s44
	v_mfma_f32_16x16x32_bf16 v[0:3], v[172:175], v[222:225], v[0:3]
	s_add_i32 s51, 0, 0x14000
	v_mfma_f32_16x16x32_bf16 v[52:55], v[148:151], v[186:189], v[52:55]
	s_add_i32 vcc_lo, s25, 2
	s_cmp_ge_u32 s50, vcc_lo
	v_mfma_f32_16x16x32_bf16 v[48:51], v[176:179], v[186:189], v[48:51]
	v_mfma_f32_16x16x32_bf16 v[36:39], v[148:151], v[208:211], v[36:39]
	v_mfma_f32_16x16x32_bf16 v[32:35], v[176:179], v[208:211], v[32:35]
	v_mfma_f32_16x16x32_bf16 v[20:23], v[148:151], v[218:221], v[20:23]
	v_mfma_f32_16x16x32_bf16 v[16:19], v[176:179], v[218:221], v[16:19]
	v_mfma_f32_16x16x32_bf16 v[4:7], v[148:151], v[226:229], v[4:7]
	v_mfma_f32_16x16x32_bf16 v[0:3], v[176:179], v[226:229], v[0:3]
	s_setprio 0
	s_barrier
	s_cbranch_scc0 .Lk473_head
	s_and_b64 vcc, exec, s[96:97]
	s_cbranch_vccz .LBB0_476
	s_barrier
